# v29 + SwiGLU epilogue tile-address chain interleaved with the first group's multiplies and exps
# speedup vs baseline: 1.0035x; 1.0035x over previous
; #define PG8_STAGE(bufoff, gbase, voff) do { _Pragma("unroll") for (int _i = 0; _i < 2; ++_i) \
;         __builtin_amdgcn_global_load_lds((const unsigned*)((const char*)(gbase) + (voff)[_i]), (LAS unsigned*)(lds + (bufoff) + ldsw + _i * 8192), 16, 0, 0); } while (0)
; #define PG8_LDA(dst, b, h) do { _Pragma("unroll") for (int m = 0; m < 4; ++m) _Pragma("unroll") for (int k = 0; k < 2; ++k) dst[m][k] = *(const LAS bf16x8*)(lds + PG8_SA(b, h) + aoff + m * 2048 + k * 1024); } while (0)
; #define PG8_LDB(dst, b, h) do { _Pragma("unroll") for (int n = 0; n < 2; ++n) _Pragma("unroll") for (int k = 0; k < 2; ++k) dst[n][k] = *(const LAS bf16x8*)(lds + PG8_SB(b, h) + boff + n * 2048 + k * 1024); } while (0)
; #define PG8_MMA(ai, bj, At, Bt) do { __builtin_amdgcn_s_setprio(1); _Pragma("unroll") for (int m = 0; m < 4; ++m) _Pragma("unroll") for (int n = 0; n < 2; ++n) _Pragma("unroll") for (int k = 0; k < 2; ++k) \
;         acc[ai][bj][m][n] = __builtin_amdgcn_mfma_f32_16x16x32_bf16(Bt[n][k], At[m][k], acc[ai][bj][m][n], 0, 0, 0); __builtin_amdgcn_s_setprio(0); } while (0)
; #define PG8_WAIT_L(n) asm volatile("s_waitcnt lgkmcnt(" #n ")" ::: "memory")
; #define PG8_BAR __builtin_amdgcn_s_barrier()
; #define PG8_SCHED __builtin_amdgcn_sched_barrier(0)
; template <class Epi>
; __device__ __forceinline__ void gemm_phase(LAS unsigned char* lds, const Gemm g, const Sched& S, const Epi& E) {
;     ...
;             PG8_LDB(B0, 0, 0); PG8_SCHED; PG8_LDA(At, 0, 0); PG8_STAGE(PG8_SA(1, 1), a1 + hstepA, voffA);
;             PG8_WAIT_L(8); PG8_BAR; PG8_WAIT_L(0); PG8_MMA(0, 0, At, B0); PG8_BAR; PG8_SCHED;
;             PG8_LDB(B1, 0, 1); PG8_STAGE(PG8_SB(0, 0), b2, voffB);
;             PG8_BAR; PG8_WAIT_L(0); PG8_MMA(0, 1, At, B1); PG8_BAR;
;             PG8_LDA(At, 0, 1); PG8_STAGE(PG8_SA(0, 0), a2, voffA);
;             PG8_BAR; PG8_WAIT_L(0); PG8_MMA(1, 0, At, B0); PG8_BAR; PG8_SCHED;
.LBB0_177:
	v_add_u32_e32 v162, s62, v148
	s_add_u32 s38, s10, s24
	ds_read_b128 v[150:153], v162
	ds_read_b128 v[154:157], v162 offset:1024
	ds_read_b128 v[158:161], v162 offset:2048
	ds_read_b128 v[162:165], v162 offset:3072
	s_addc_u32 s39, s11, s25
	s_add_u32 s38, s38, 0x100
	s_addc_u32 s39, s39, 0
	s_add_u32 s71, s9, s24
	s_addc_u32 s80, s51, s25
	s_cmpk_eq_i32 s24, 0xf00
	s_cselect_b32 s53, s19, s39
	s_cselect_b32 s52, s66, s38
	s_cselect_b32 s39, s17, s80
	s_cselect_b32 s38, s67, s71
	v_lshl_add_u64 v[190:191], v[144:145], 0, s[24:25]
	s_add_i32 m0, s35, 0xc000
	ds_read_b128 v[166:169], v149
	ds_read_b128 v[170:173], v149 offset:1024
	ds_read_b128 v[174:177], v149 offset:2048
	ds_read_b128 v[178:181], v149 offset:3072
	ds_read_b128 v[182:185], v149 offset:4096
	ds_read_b128 v[186:189], v149 offset:5120
	ds_read_b128 v[194:197], v149 offset:6144
	ds_read_b128 v[198:201], v149 offset:7168
	global_load_lds_dwordx4 v[190:191], off
	v_lshl_add_u64 v[190:191], v[146:147], 0, s[24:25]
	s_add_i32 m0, s35, 0xe000
	s_nop 0
	global_load_lds_dwordx4 v[190:191], off
	s_waitcnt lgkmcnt(8)
	s_barrier
	s_waitcnt lgkmcnt(0)
	s_setprio 1
	s_waitcnt lgkmcnt(0)
	v_mfma_f32_16x16x32_bf16 v[124:127], v[150:153], v[166:169], v[124:127]
	v_mfma_f32_16x16x32_bf16 v[120:123], v[158:161], v[166:169], v[120:123]
	v_mfma_f32_16x16x32_bf16 v[116:119], v[150:153], v[174:177], v[116:119]
	v_mfma_f32_16x16x32_bf16 v[112:115], v[158:161], v[174:177], v[112:115]
	v_mfma_f32_16x16x32_bf16 v[108:111], v[150:153], v[182:185], v[108:111]
	v_mfma_f32_16x16x32_bf16 v[104:107], v[158:161], v[182:185], v[104:107]
	v_mfma_f32_16x16x32_bf16 v[100:103], v[150:153], v[194:197], v[100:103]
	v_mfma_f32_16x16x32_bf16 v[96:99], v[158:161], v[194:197], v[96:99]
	v_mfma_f32_16x16x32_bf16 v[124:127], v[154:157], v[170:173], v[124:127]
	v_mfma_f32_16x16x32_bf16 v[120:123], v[162:165], v[170:173], v[120:123]
	v_mfma_f32_16x16x32_bf16 v[116:119], v[154:157], v[178:181], v[116:119]
	v_mfma_f32_16x16x32_bf16 v[112:115], v[162:165], v[178:181], v[112:115]
	v_mfma_f32_16x16x32_bf16 v[108:111], v[154:157], v[186:189], v[108:111]
	v_mfma_f32_16x16x32_bf16 v[104:107], v[162:165], v[186:189], v[104:107]
	v_mfma_f32_16x16x32_bf16 v[100:103], v[154:157], v[198:201], v[100:103]
	v_mfma_f32_16x16x32_bf16 v[96:99], v[162:165], v[198:201], v[96:99]
	s_setprio 0
	s_barrier
	v_add_u32_e32 v190, s63, v148
	s_add_i32 s71, s62, s1
	ds_read_b128 v[202:205], v190
	ds_read_b128 v[206:209], v190 offset:1024
	ds_read_b128 v[210:213], v190 offset:2048
	ds_read_b128 v[214:217], v190 offset:3072
	v_lshl_add_u64 v[190:191], s[38:39], 0, v[130:131]
	s_mov_b32 m0, s71
	v_lshl_add_u64 v[218:219], s[38:39], 0, v[128:129]
	global_load_lds_dwordx4 v[190:191], off
	s_add_i32 m0, s71, 0x2000
	s_nop 0
	global_load_lds_dwordx4 v[218:219], off
	s_barrier
	s_waitcnt lgkmcnt(0)
	s_setprio 1
	s_waitcnt lgkmcnt(0)
	v_mfma_f32_16x16x32_bf16 v[92:95], v[202:205], v[166:169], v[92:95]
	v_mfma_f32_16x16x32_bf16 v[88:91], v[210:213], v[166:169], v[88:91]
	v_mfma_f32_16x16x32_bf16 v[84:87], v[202:205], v[174:177], v[84:87]
	v_mfma_f32_16x16x32_bf16 v[80:83], v[210:213], v[174:177], v[80:83]
	v_mfma_f32_16x16x32_bf16 v[76:79], v[202:205], v[182:185], v[76:79]
	v_mfma_f32_16x16x32_bf16 v[72:75], v[210:213], v[182:185], v[72:75]
	v_mfma_f32_16x16x32_bf16 v[68:71], v[202:205], v[194:197], v[68:71]
	v_mfma_f32_16x16x32_bf16 v[64:67], v[210:213], v[194:197], v[64:67]
	v_mfma_f32_16x16x32_bf16 v[92:95], v[206:209], v[170:173], v[92:95]
	v_mfma_f32_16x16x32_bf16 v[88:91], v[214:217], v[170:173], v[88:91]
	v_mfma_f32_16x16x32_bf16 v[84:87], v[206:209], v[178:181], v[84:87]
	v_mfma_f32_16x16x32_bf16 v[80:83], v[214:217], v[178:181], v[80:83]
	v_mfma_f32_16x16x32_bf16 v[76:79], v[206:209], v[186:189], v[76:79]
	v_mfma_f32_16x16x32_bf16 v[72:75], v[214:217], v[186:189], v[72:75]
	v_mfma_f32_16x16x32_bf16 v[68:71], v[206:209], v[198:201], v[68:71]
	v_mfma_f32_16x16x32_bf16 v[64:67], v[214:217], v[198:201], v[64:67]
	s_setprio 0
	s_mov_b32 m0, s35
	v_lshl_add_u64 v[220:221], s[52:53], 0, v[130:131]
	s_barrier
	ds_read_b128 v[166:169], v149 offset:16384
	ds_read_b128 v[170:173], v149 offset:17408
	ds_read_b128 v[174:177], v149 offset:18432
	ds_read_b128 v[178:181], v149 offset:19456
	ds_read_b128 v[182:185], v149 offset:20480
	ds_read_b128 v[186:189], v149 offset:21504
	ds_read_b128 v[194:197], v149 offset:22528
	ds_read_b128 v[198:201], v149 offset:23552
	global_load_lds_dwordx4 v[220:221], off
	v_lshl_add_u64 v[222:223], s[52:53], 0, v[128:129]
	s_mov_b32 m0, s43
	s_nop 0
	global_load_lds_dwordx4 v[222:223], off
	s_barrier
	s_waitcnt lgkmcnt(0)
	s_setprio 1
	s_waitcnt lgkmcnt(0)
	v_mfma_f32_16x16x32_bf16 v[60:63], v[150:153], v[166:169], v[60:63]
	v_mfma_f32_16x16x32_bf16 v[56:59], v[158:161], v[166:169], v[56:59]
	v_mfma_f32_16x16x32_bf16 v[52:55], v[150:153], v[174:177], v[52:55]
	v_mfma_f32_16x16x32_bf16 v[48:51], v[158:161], v[174:177], v[48:51]
	v_mfma_f32_16x16x32_bf16 v[44:47], v[150:153], v[182:185], v[44:47]
	v_mfma_f32_16x16x32_bf16 v[40:43], v[158:161], v[182:185], v[40:43]
	v_mfma_f32_16x16x32_bf16 v[36:39], v[150:153], v[194:197], v[36:39]
	v_mfma_f32_16x16x32_bf16 v[32:35], v[158:161], v[194:197], v[32:35]
	v_mfma_f32_16x16x32_bf16 v[60:63], v[154:157], v[170:173], v[60:63]
	v_mfma_f32_16x16x32_bf16 v[56:59], v[162:165], v[170:173], v[56:59]
	v_mfma_f32_16x16x32_bf16 v[52:55], v[154:157], v[178:181], v[52:55]
	v_mfma_f32_16x16x32_bf16 v[48:51], v[162:165], v[178:181], v[48:51]
	v_mfma_f32_16x16x32_bf16 v[44:47], v[154:157], v[186:189], v[44:47]
	v_mfma_f32_16x16x32_bf16 v[40:43], v[162:165], v[186:189], v[40:43]
	v_mfma_f32_16x16x32_bf16 v[36:39], v[154:157], v[198:201], v[36:39]
	v_mfma_f32_16x16x32_bf16 v[32:35], v[162:165], v[198:201], v[32:35]
	s_setprio 0
	s_barrier
; #define PG8_STAGE(bufoff, gbase, voff) do { _Pragma("unroll") for (int _i = 0; _i < 2; ++_i) \
;         __builtin_amdgcn_global_load_lds((const unsigned*)((const char*)(gbase) + (voff)[_i]), (LAS unsigned*)(lds + (bufoff) + ldsw + _i * 8192), 16, 0, 0); } while (0)
; #define PG8_LDA(dst, b, h) do { _Pragma("unroll") for (int m = 0; m < 4; ++m) _Pragma("unroll") for (int k = 0; k < 2; ++k) dst[m][k] = *(const LAS bf16x8*)(lds + PG8_SA(b, h) + aoff + m * 2048 + k * 1024); } while (0)
; #define PG8_LDB(dst, b, h) do { _Pragma("unroll") for (int n = 0; n < 2; ++n) _Pragma("unroll") for (int k = 0; k < 2; ++k) dst[n][k] = *(const LAS bf16x8*)(lds + PG8_SB(b, h) + boff + n * 2048 + k * 1024); } while (0)
; #define PG8_MMA(ai, bj, At, Bt) do { __builtin_amdgcn_s_setprio(1); _Pragma("unroll") for (int m = 0; m < 4; ++m) _Pragma("unroll") for (int n = 0; n < 2; ++n) _Pragma("unroll") for (int k = 0; k < 2; ++k) \
;         acc[ai][bj][m][n] = __builtin_amdgcn_mfma_f32_16x16x32_bf16(Bt[n][k], At[m][k], acc[ai][bj][m][n], 0, 0, 0); __builtin_amdgcn_s_setprio(0); } while (0)
; #define PG8_WAIT_V(n) asm volatile("s_waitcnt vmcnt(" #n ")" ::: "memory")
; #define PG8_WAIT_L(n) asm volatile("s_waitcnt lgkmcnt(" #n ")" ::: "memory")
; #define PG8_BAR __builtin_amdgcn_s_barrier()
; #define PG8_SCHED __builtin_amdgcn_sched_barrier(0)
; template <class Epi>
; __device__ __forceinline__ void gemm_phase(LAS unsigned char* lds, const Gemm g, const Sched& S, const Epi& E) {
;     ...
;             PG8_STAGE(PG8_SB(0, 1), b2 + hstepB, voffB);
;             PG8_WAIT_V(6); PG8_BAR; PG8_MMA(1, 1, At, B1); PG8_BAR;
;             PG8_LDB(B0, 1, 0); PG8_SCHED; PG8_LDA(At, 1, 0); PG8_STAGE(PG8_SA(0, 1), a2 + hstepA, voffA);
;             PG8_WAIT_L(8); PG8_BAR; PG8_WAIT_L(0); PG8_MMA(0, 0, At, B0); PG8_BAR; PG8_SCHED;
;             PG8_LDB(B1, 1, 1); PG8_STAGE(PG8_SB(1, 0), b3, voffB);
;             PG8_BAR; PG8_WAIT_L(0); PG8_MMA(0, 1, At, B1); PG8_BAR;
;             PG8_LDA(At, 1, 1); PG8_STAGE(PG8_SA(1, 0), a3, voffA);
	s_add_u32 s80, s38, 0x80000
	s_addc_u32 s81, s39, 0
	s_add_i32 s71, s63, s1
	v_lshl_add_u64 v[150:151], s[80:81], 0, v[130:131]
	s_mov_b32 m0, s71
	s_nop 0
	global_load_lds_dwordx4 v[150:151], off
	v_lshl_add_u64 v[150:151], s[80:81], 0, v[128:129]
	s_add_i32 m0, s71, 0x2000
	s_nop 0
	global_load_lds_dwordx4 v[150:151], off
	s_waitcnt vmcnt(6)
	s_barrier
	s_setprio 1
	v_mfma_f32_16x16x32_bf16 v[28:31], v[202:205], v[166:169], v[28:31]
	v_mfma_f32_16x16x32_bf16 v[24:27], v[210:213], v[166:169], v[24:27]
	v_mfma_f32_16x16x32_bf16 v[20:23], v[202:205], v[174:177], v[20:23]
	v_mfma_f32_16x16x32_bf16 v[16:19], v[210:213], v[174:177], v[16:19]
	v_mfma_f32_16x16x32_bf16 v[12:15], v[202:205], v[182:185], v[12:15]
	v_mfma_f32_16x16x32_bf16 v[8:11], v[210:213], v[182:185], v[8:11]
	v_mfma_f32_16x16x32_bf16 v[4:7], v[202:205], v[194:197], v[4:7]
	v_mfma_f32_16x16x32_bf16 v[0:3], v[210:213], v[194:197], v[0:3]
	v_mfma_f32_16x16x32_bf16 v[28:31], v[206:209], v[170:173], v[28:31]
	v_mfma_f32_16x16x32_bf16 v[24:27], v[214:217], v[170:173], v[24:27]
	v_mfma_f32_16x16x32_bf16 v[20:23], v[206:209], v[178:181], v[20:23]
	v_mfma_f32_16x16x32_bf16 v[16:19], v[214:217], v[178:181], v[16:19]
	v_mfma_f32_16x16x32_bf16 v[12:15], v[206:209], v[186:189], v[12:15]
	v_mfma_f32_16x16x32_bf16 v[8:11], v[214:217], v[186:189], v[8:11]
	v_mfma_f32_16x16x32_bf16 v[4:7], v[206:209], v[198:201], v[4:7]
	v_mfma_f32_16x16x32_bf16 v[0:3], v[214:217], v[198:201], v[0:3]
	s_setprio 0
	s_add_i32 s71, 0, 0x18000
	v_add_u32_e32 v162, s71, v148
	s_barrier
	ds_read_b128 v[150:153], v162
	ds_read_b128 v[154:157], v162 offset:1024
	ds_read_b128 v[158:161], v162 offset:2048
	ds_read_b128 v[162:165], v162 offset:3072
	s_add_u32 s52, s52, 0x80000
	s_addc_u32 s53, s53, 0
	s_mov_b32 m0, s54
	v_lshl_add_u64 v[202:203], s[52:53], 0, v[130:131]
	ds_read_b128 v[166:169], v149 offset:32768
	ds_read_b128 v[170:173], v149 offset:33792
	ds_read_b128 v[174:177], v149 offset:34816
	ds_read_b128 v[178:181], v149 offset:35840
	ds_read_b128 v[182:185], v149 offset:36864
	ds_read_b128 v[186:189], v149 offset:37888
	ds_read_b128 v[194:197], v149 offset:38912
	ds_read_b128 v[198:201], v149 offset:39936
	global_load_lds_dwordx4 v[202:203], off
	v_lshl_add_u64 v[202:203], s[52:53], 0, v[128:129]
	s_mov_b32 m0, s55
	s_nop 0
	global_load_lds_dwordx4 v[202:203], off
	s_waitcnt lgkmcnt(8)
	s_barrier
	s_waitcnt lgkmcnt(0)
	s_setprio 1
	s_waitcnt lgkmcnt(0)
	v_mfma_f32_16x16x32_bf16 v[124:127], v[150:153], v[166:169], v[124:127]
	v_mfma_f32_16x16x32_bf16 v[120:123], v[158:161], v[166:169], v[120:123]
	v_mfma_f32_16x16x32_bf16 v[116:119], v[150:153], v[174:177], v[116:119]
	v_mfma_f32_16x16x32_bf16 v[112:115], v[158:161], v[174:177], v[112:115]
	v_mfma_f32_16x16x32_bf16 v[108:111], v[150:153], v[182:185], v[108:111]
	v_mfma_f32_16x16x32_bf16 v[104:107], v[158:161], v[182:185], v[104:107]
	v_mfma_f32_16x16x32_bf16 v[100:103], v[150:153], v[194:197], v[100:103]
	v_mfma_f32_16x16x32_bf16 v[96:99], v[158:161], v[194:197], v[96:99]
	v_mfma_f32_16x16x32_bf16 v[124:127], v[154:157], v[170:173], v[124:127]
	v_mfma_f32_16x16x32_bf16 v[120:123], v[162:165], v[170:173], v[120:123]
	v_mfma_f32_16x16x32_bf16 v[116:119], v[154:157], v[178:181], v[116:119]
	v_mfma_f32_16x16x32_bf16 v[112:115], v[162:165], v[178:181], v[112:115]
	v_mfma_f32_16x16x32_bf16 v[108:111], v[154:157], v[186:189], v[108:111]
	v_mfma_f32_16x16x32_bf16 v[104:107], v[162:165], v[186:189], v[104:107]
	v_mfma_f32_16x16x32_bf16 v[100:103], v[154:157], v[198:201], v[100:103]
	v_mfma_f32_16x16x32_bf16 v[96:99], v[162:165], v[198:201], v[96:99]
	s_setprio 0
	s_barrier
	s_add_i32 s52, 0, 0x1c000
	s_add_i32 s53, s71, s1
	v_add_u32_e32 v214, s52, v148
	v_lshl_add_u64 v[190:191], v[190:191], 0, s[14:15]
	s_mov_b32 m0, s53
	ds_read_b128 v[202:205], v214
	ds_read_b128 v[206:209], v214 offset:1024
	ds_read_b128 v[210:213], v214 offset:2048
	ds_read_b128 v[214:217], v214 offset:3072
	global_load_lds_dwordx4 v[190:191], off
	v_lshl_add_u64 v[190:191], v[218:219], 0, s[14:15]
	s_add_i32 m0, s53, 0x2000
	s_nop 0
	global_load_lds_dwordx4 v[190:191], off
	s_barrier
	s_waitcnt lgkmcnt(0)
	s_setprio 1
	s_waitcnt lgkmcnt(0)
	v_mfma_f32_16x16x32_bf16 v[92:95], v[202:205], v[166:169], v[92:95]
	v_mfma_f32_16x16x32_bf16 v[88:91], v[210:213], v[166:169], v[88:91]
	v_mfma_f32_16x16x32_bf16 v[84:87], v[202:205], v[174:177], v[84:87]
	v_mfma_f32_16x16x32_bf16 v[80:83], v[210:213], v[174:177], v[80:83]
	v_mfma_f32_16x16x32_bf16 v[76:79], v[202:205], v[182:185], v[76:79]
	v_mfma_f32_16x16x32_bf16 v[72:75], v[210:213], v[182:185], v[72:75]
	v_mfma_f32_16x16x32_bf16 v[68:71], v[202:205], v[194:197], v[68:71]
	v_mfma_f32_16x16x32_bf16 v[64:67], v[210:213], v[194:197], v[64:67]
	v_mfma_f32_16x16x32_bf16 v[92:95], v[206:209], v[170:173], v[92:95]
	v_mfma_f32_16x16x32_bf16 v[88:91], v[214:217], v[170:173], v[88:91]
	v_mfma_f32_16x16x32_bf16 v[84:87], v[206:209], v[178:181], v[84:87]
	v_mfma_f32_16x16x32_bf16 v[80:83], v[214:217], v[178:181], v[80:83]
	v_mfma_f32_16x16x32_bf16 v[76:79], v[206:209], v[186:189], v[76:79]
	v_mfma_f32_16x16x32_bf16 v[72:75], v[214:217], v[186:189], v[72:75]
	v_mfma_f32_16x16x32_bf16 v[68:71], v[206:209], v[198:201], v[68:71]
	v_mfma_f32_16x16x32_bf16 v[64:67], v[214:217], v[198:201], v[64:67]
	s_setprio 0
	s_mov_b32 m0, s59
	v_lshl_add_u64 v[190:191], v[220:221], 0, s[14:15]
	s_barrier
	ds_read_b128 v[166:169], v149 offset:49152
	ds_read_b128 v[170:173], v149 offset:50176
	ds_read_b128 v[174:177], v149 offset:51200
	ds_read_b128 v[178:181], v149 offset:52224
	ds_read_b128 v[182:185], v149 offset:53248
	ds_read_b128 v[186:189], v149 offset:54272
	ds_read_b128 v[194:197], v149 offset:55296
	ds_read_b128 v[198:201], v149 offset:56320
	global_load_lds_dwordx4 v[190:191], off
	v_lshl_add_u64 v[190:191], v[222:223], 0, s[14:15]
	s_mov_b32 m0, s61
	s_nop 0
	global_load_lds_dwordx4 v[190:191], off
	s_barrier
; __device__ __forceinline__ unsigned cvt_pk_bf16(float lo, float hi) { unsigned r; asm volatile("v_cvt_pk_bf16_f32 %0, %1, %2" : "=v"(r) : "v"(lo), "v"(hi)); return r; }
; #define PG8_STAGE(bufoff, gbase, voff) do { _Pragma("unroll") for (int _i = 0; _i < 2; ++_i) \
;         __builtin_amdgcn_global_load_lds((const unsigned*)((const char*)(gbase) + (voff)[_i]), (LAS unsigned*)(lds + (bufoff) + ldsw + _i * 8192), 16, 0, 0); } while (0)
; #define PG8_MMA(ai, bj, At, Bt) do { __builtin_amdgcn_s_setprio(1); _Pragma("unroll") for (int m = 0; m < 4; ++m) _Pragma("unroll") for (int n = 0; n < 2; ++n) _Pragma("unroll") for (int k = 0; k < 2; ++k) \
;         acc[ai][bj][m][n] = __builtin_amdgcn_mfma_f32_16x16x32_bf16(Bt[n][k], At[m][k], acc[ai][bj][m][n], 0, 0, 0); __builtin_amdgcn_s_setprio(0); } while (0)
; #define PG8_WAIT_V(n) asm volatile("s_waitcnt vmcnt(" #n ")" ::: "memory")
; #define PG8_WAIT_L(n) asm volatile("s_waitcnt lgkmcnt(" #n ")" ::: "memory")
; #define PG8_BAR __builtin_amdgcn_s_barrier()
; #define PG8_SCHED __builtin_amdgcn_sched_barrier(0)
; template <class Epi>
; __device__ __forceinline__ void gemm_phase(LAS unsigned char* lds, const Gemm g, const Sched& S, const Epi& E) {
;     ...
;             PG8_BAR; PG8_WAIT_L(0); PG8_MMA(1, 0, At, B0); PG8_BAR; PG8_SCHED;
;             PG8_STAGE(PG8_SB(1, 1), b3 + hstepB, voffB);
;             PG8_WAIT_V(6); PG8_BAR; PG8_MMA(1, 1, At, B1); PG8_BAR;
;     __device__ __forceinline__ void operator()(AccRef acc, const Unit& u, int wr, int wc, int fr, int fq) const {
;     ...
;         for (int ai = 0; ai < 2; ++ai)
; #pragma unroll
;             for (int m = 0; m < 4; ++m) { const size_t row = (size_t)u.pm * 256 + ai * 128 + wr * 64 + m * 16 + fr; float o[8];
; #pragma unroll
;                 for (int bj = 0; bj < 2; ++bj) { const f32x4 gg = acc[ai][bj][m][0], uu = acc[ai][bj][m][1];
; #pragma unroll
;                     for (int j = 0; j < 4; ++j) o[4 * bj + j] = gg[j] * __builtin_amdgcn_rcpf(1.0f + __expf(-gg[j])) * uu[j]; }
;                 u32x4 w; w.x = cvt_pk_bf16(o[0], o[1]); w.y = cvt_pk_bf16(o[2], o[3]); w.z = cvt_pk_bf16(o[4], o[5]); w.w = cvt_pk_bf16(o[6], o[7]);
;                 *(u32x4*)(act + row * FF_ + (u.pn * 4 + wc) * 32 + 8 * fq) = w; }
	s_waitcnt lgkmcnt(0)
	s_setprio 1
	s_waitcnt lgkmcnt(0)
	v_mfma_f32_16x16x32_bf16 v[60:63], v[150:153], v[166:169], v[60:63]
	v_mfma_f32_16x16x32_bf16 v[56:59], v[158:161], v[166:169], v[56:59]
	v_mfma_f32_16x16x32_bf16 v[52:55], v[150:153], v[174:177], v[52:55]
	v_mfma_f32_16x16x32_bf16 v[48:51], v[158:161], v[174:177], v[48:51]
	v_mfma_f32_16x16x32_bf16 v[44:47], v[150:153], v[182:185], v[44:47]
	v_mfma_f32_16x16x32_bf16 v[40:43], v[158:161], v[182:185], v[40:43]
	v_mfma_f32_16x16x32_bf16 v[36:39], v[150:153], v[194:197], v[36:39]
	v_mfma_f32_16x16x32_bf16 v[32:35], v[158:161], v[194:197], v[32:35]
	v_mfma_f32_16x16x32_bf16 v[60:63], v[154:157], v[170:173], v[60:63]
	v_mfma_f32_16x16x32_bf16 v[56:59], v[162:165], v[170:173], v[56:59]
	v_mfma_f32_16x16x32_bf16 v[52:55], v[154:157], v[178:181], v[52:55]
	v_mfma_f32_16x16x32_bf16 v[48:51], v[162:165], v[178:181], v[48:51]
	v_mfma_f32_16x16x32_bf16 v[44:47], v[154:157], v[186:189], v[44:47]
	v_mfma_f32_16x16x32_bf16 v[40:43], v[162:165], v[186:189], v[40:43]
	v_mfma_f32_16x16x32_bf16 v[36:39], v[154:157], v[198:201], v[36:39]
	v_mfma_f32_16x16x32_bf16 v[32:35], v[162:165], v[198:201], v[32:35]
	s_setprio 0
	s_barrier
	s_add_u32 s38, s38, 0x80080
	s_addc_u32 s39, s39, 0
	s_add_i32 s52, s52, s1
	v_lshl_add_u64 v[150:151], s[38:39], 0, v[130:131]
	s_mov_b32 m0, s52
	s_nop 0
	global_load_lds_dwordx4 v[150:151], off
	v_lshl_add_u64 v[150:151], s[38:39], 0, v[128:129]
	s_add_i32 m0, s52, 0x2000
	s_nop 0
	global_load_lds_dwordx4 v[150:151], off
	s_waitcnt vmcnt(6)
	s_barrier
	s_setprio 1
	v_mfma_f32_16x16x32_bf16 v[28:31], v[202:205], v[166:169], v[28:31]
	v_mfma_f32_16x16x32_bf16 v[24:27], v[210:213], v[166:169], v[24:27]
	v_mfma_f32_16x16x32_bf16 v[20:23], v[202:205], v[174:177], v[20:23]
	v_mfma_f32_16x16x32_bf16 v[16:19], v[210:213], v[174:177], v[16:19]
	v_mfma_f32_16x16x32_bf16 v[12:15], v[202:205], v[182:185], v[12:15]
	v_mfma_f32_16x16x32_bf16 v[8:11], v[210:213], v[182:185], v[8:11]
	v_mfma_f32_16x16x32_bf16 v[4:7], v[202:205], v[194:197], v[4:7]
	v_mfma_f32_16x16x32_bf16 v[0:3], v[210:213], v[194:197], v[0:3]
	v_mfma_f32_16x16x32_bf16 v[28:31], v[206:209], v[170:173], v[28:31]
	v_mfma_f32_16x16x32_bf16 v[24:27], v[214:217], v[170:173], v[24:27]
	v_mfma_f32_16x16x32_bf16 v[20:23], v[206:209], v[178:181], v[20:23]
	v_mfma_f32_16x16x32_bf16 v[16:19], v[214:217], v[178:181], v[16:19]
	v_mfma_f32_16x16x32_bf16 v[12:15], v[206:209], v[186:189], v[12:15]
	v_mfma_f32_16x16x32_bf16 v[8:11], v[214:217], v[186:189], v[8:11]
	v_mfma_f32_16x16x32_bf16 v[4:7], v[206:209], v[198:201], v[4:7]
	v_mfma_f32_16x16x32_bf16 v[0:3], v[214:217], v[198:201], v[0:3]
	s_setprio 0
	s_add_i32 s70, s70, 2
	s_add_u32 s24, s24, 0x100
	s_addc_u32 s25, s25, 0
	s_cmp_gt_u32 s70, 29
	s_barrier
	s_cbranch_scc0 .LBB0_177
	v_mov_b32_e32 v170, 0xbfb8aa3b
	v_mov_b32_e32 v172, 1.0
	v_mov_b64_e32 v[176:177], 0
	v_mov_b64_e32 v[178:179], 0
	v_pk_mul_f32 v[162:163], v[124:125], v[170:171] op_sel_hi:[1,0]
	s_add_u32 s24, s9, 0xffffff00
	v_pk_mul_f32 v[164:165], v[126:127], v[170:171] op_sel_hi:[1,0]
	s_addc_u32 s25, s51, -1
	v_pk_mul_f32 v[166:167], v[92:93], v[170:171] op_sel_hi:[1,0]
	s_ashr_i32 s9, s8, 31
	v_pk_mul_f32 v[168:169], v[94:95], v[170:171] op_sel_hi:[1,0]
	s_lshl_b64 s[38:39], s[8:9], 8
	v_exp_f32_e32 v162, v162
	v_lshl_add_u64 v[144:145], v[134:135], 0, s[38:39]
	v_exp_f32_e32 v163, v163
	v_mov_b64_e32 v[146:147], s[44:45]
	v_exp_f32_e32 v164, v164
	v_mad_u64_u32 v[146:147], s[52:53], v144, s64, v[146:147]
	v_exp_f32_e32 v165, v165
	s_lshl_b32 s9, s57, 7
	v_exp_f32_e32 v166, v166
	v_mov_b32_e32 v144, v147
	v_exp_f32_e32 v167, v167
	s_or_b32 s38, s9, s58
	v_exp_f32_e32 v168, v168
	v_mad_u64_u32 v[144:145], s[52:53], v145, s64, v[144:145]
	v_exp_f32_e32 v169, v169
	s_ashr_i32 s39, s38, 31
	v_mov_b32_e32 v147, v144
	v_lshl_add_u64 v[144:145], s[38:39], 1, v[146:147]
	v_lshl_add_u64 v[144:145], v[144:145], 0, v[132:133]
	v_pk_add_f32 v[162:163], v[162:163], v[172:173] op_sel_hi:[1,0]
	v_pk_add_f32 v[164:165], v[164:165], v[172:173] op_sel_hi:[1,0]
	v_pk_add_f32 v[166:167], v[166:167], v[172:173] op_sel_hi:[1,0]
	v_pk_add_f32 v[168:169], v[168:169], v[172:173] op_sel_hi:[1,0]
	v_rcp_f32_e32 v162, v162
	v_rcp_f32_e32 v163, v163
	v_rcp_f32_e32 v164, v164
	v_rcp_f32_e32 v165, v165
	v_rcp_f32_e32 v166, v166
	v_rcp_f32_e32 v167, v167
	v_rcp_f32_e32 v168, v168
	v_rcp_f32_e32 v169, v169
	v_pk_mul_f32 v[162:163], v[124:125], v[162:163]
	v_pk_mul_f32 v[164:165], v[126:127], v[164:165]
	v_pk_mul_f32 v[166:167], v[92:93], v[166:167]
	v_pk_mul_f32 v[168:169], v[94:95], v[168:169]
	v_pk_mul_f32 v[162:163], v[120:121], v[162:163]
	v_pk_mul_f32 v[164:165], v[122:123], v[164:165]
	v_pk_mul_f32 v[166:167], v[88:89], v[166:167]
	v_pk_mul_f32 v[168:169], v[90:91], v[168:169]
	v_cvt_pk_bf16_f32 v150, v162, v163
	v_cvt_pk_bf16_f32 v151, v164, v165
	v_cvt_pk_bf16_f32 v152, v166, v167
	v_cvt_pk_bf16_f32 v153, v168, v169
	global_store_dwordx4 v[144:145], v[150:153], off
	s_mov_b32 s9, 0x2c000
	v_add_co_u32_e32 v146, vcc, s9, v144
	s_nop 0
	v_addc_co_u32_e32 v147, vcc, 0, v145, vcc
	v_pk_mul_f32 v[162:163], v[116:117], v[170:171] op_sel_hi:[1,0]
	v_pk_mul_f32 v[164:165], v[118:119], v[170:171] op_sel_hi:[1,0]
	v_pk_mul_f32 v[166:167], v[84:85], v[170:171] op_sel_hi:[1,0]
	v_pk_mul_f32 v[168:169], v[86:87], v[170:171] op_sel_hi:[1,0]
	v_exp_f32_e32 v162, v162
	v_exp_f32_e32 v163, v163
	v_exp_f32_e32 v164, v164
	v_exp_f32_e32 v165, v165
	v_exp_f32_e32 v166, v166
	v_exp_f32_e32 v167, v167
	v_exp_f32_e32 v168, v168
	v_exp_f32_e32 v169, v169
	v_pk_add_f32 v[162:163], v[162:163], v[172:173] op_sel_hi:[1,0]
	v_pk_add_f32 v[164:165], v[164:165], v[172:173] op_sel_hi:[1,0]
; __device__ __forceinline__ unsigned cvt_pk_bf16(float lo, float hi) { unsigned r; asm volatile("v_cvt_pk_bf16_f32 %0, %1, %2" : "=v"(r) : "v"(lo), "v"(hi)); return r; }
; template <class Epi>
; __device__ __forceinline__ void gemm_phase(LAS unsigned char* lds, const Gemm g, const Sched& S, const Epi& E) {
;     ...
; #pragma unroll
;         for (int a = 0; a < 2; ++a)
; #pragma unroll
;             for (int b = 0; b < 2; ++b)
; #pragma unroll
;                 for (int m = 0; m < 4; ++m)
; #pragma unroll
;                     for (int n = 0; n < 2; ++n) acc[a][b][m][n] = (f32x4){0.f, 0.f, 0.f, 0.f};
;     __device__ __forceinline__ void operator()(AccRef acc, const Unit& u, int wr, int wc, int fr, int fq) const {
;     ...
;         for (int ai = 0; ai < 2; ++ai)
; #pragma unroll
;             for (int m = 0; m < 4; ++m) { const size_t row = (size_t)u.pm * 256 + ai * 128 + wr * 64 + m * 16 + fr; float o[8];
; #pragma unroll
;                 for (int bj = 0; bj < 2; ++bj) { const f32x4 gg = acc[ai][bj][m][0], uu = acc[ai][bj][m][1];
; #pragma unroll
;                     for (int j = 0; j < 4; ++j) o[4 * bj + j] = gg[j] * __builtin_amdgcn_rcpf(1.0f + __expf(-gg[j])) * uu[j]; }
;                 u32x4 w; w.x = cvt_pk_bf16(o[0], o[1]); w.y = cvt_pk_bf16(o[2], o[3]); w.z = cvt_pk_bf16(o[4], o[5]); w.w = cvt_pk_bf16(o[6], o[7]);
;                 *(u32x4*)(act + row * FF_ + (u.pn * 4 + wc) * 32 + 8 * fq) = w; }
	v_pk_add_f32 v[166:167], v[166:167], v[172:173] op_sel_hi:[1,0]
	v_pk_add_f32 v[168:169], v[168:169], v[172:173] op_sel_hi:[1,0]
	v_rcp_f32_e32 v162, v162
	v_rcp_f32_e32 v163, v163
	v_rcp_f32_e32 v164, v164
	v_rcp_f32_e32 v165, v165
	v_rcp_f32_e32 v166, v166
	v_rcp_f32_e32 v167, v167
	v_rcp_f32_e32 v168, v168
	v_rcp_f32_e32 v169, v169
	v_pk_mul_f32 v[162:163], v[116:117], v[162:163]
	v_pk_mul_f32 v[164:165], v[118:119], v[164:165]
	v_pk_mul_f32 v[166:167], v[84:85], v[166:167]
	v_pk_mul_f32 v[168:169], v[86:87], v[168:169]
	v_pk_mul_f32 v[162:163], v[112:113], v[162:163]
	v_pk_mul_f32 v[164:165], v[114:115], v[164:165]
	v_pk_mul_f32 v[166:167], v[80:81], v[166:167]
	v_pk_mul_f32 v[168:169], v[82:83], v[168:169]
	v_cvt_pk_bf16_f32 v150, v162, v163
	v_cvt_pk_bf16_f32 v151, v164, v165
	v_cvt_pk_bf16_f32 v152, v166, v167
	v_cvt_pk_bf16_f32 v153, v168, v169
	global_store_dwordx4 v[146:147], v[150:153], off
	v_mfma_f32_32x32x16_bf16 v[80:95], v[176:179], v[176:179], 0
	v_mfma_f32_32x32x16_bf16 v[112:127], v[176:179], v[176:179], 0
	s_mov_b32 s9, 0x58000
	v_add_co_u32_e32 v146, vcc, s9, v144
	s_nop 0
	v_addc_co_u32_e32 v147, vcc, 0, v145, vcc
	v_pk_mul_f32 v[162:163], v[108:109], v[170:171] op_sel_hi:[1,0]
	v_pk_mul_f32 v[164:165], v[110:111], v[170:171] op_sel_hi:[1,0]
	v_pk_mul_f32 v[166:167], v[76:77], v[170:171] op_sel_hi:[1,0]
	v_pk_mul_f32 v[168:169], v[78:79], v[170:171] op_sel_hi:[1,0]
	v_exp_f32_e32 v162, v162
	v_exp_f32_e32 v163, v163
	v_exp_f32_e32 v164, v164
	v_exp_f32_e32 v165, v165
	v_exp_f32_e32 v166, v166
	v_exp_f32_e32 v167, v167
	v_exp_f32_e32 v168, v168
	v_exp_f32_e32 v169, v169
	v_pk_add_f32 v[162:163], v[162:163], v[172:173] op_sel_hi:[1,0]
	v_pk_add_f32 v[164:165], v[164:165], v[172:173] op_sel_hi:[1,0]
	v_pk_add_f32 v[166:167], v[166:167], v[172:173] op_sel_hi:[1,0]
	v_pk_add_f32 v[168:169], v[168:169], v[172:173] op_sel_hi:[1,0]
	v_rcp_f32_e32 v162, v162
	v_rcp_f32_e32 v163, v163
	v_rcp_f32_e32 v164, v164
	v_rcp_f32_e32 v165, v165
	v_rcp_f32_e32 v166, v166
	v_rcp_f32_e32 v167, v167
	v_rcp_f32_e32 v168, v168
	v_rcp_f32_e32 v169, v169
	v_pk_mul_f32 v[162:163], v[108:109], v[162:163]
	v_pk_mul_f32 v[164:165], v[110:111], v[164:165]
	v_pk_mul_f32 v[166:167], v[76:77], v[166:167]
	v_pk_mul_f32 v[168:169], v[78:79], v[168:169]
	v_pk_mul_f32 v[162:163], v[104:105], v[162:163]
	v_pk_mul_f32 v[164:165], v[106:107], v[164:165]
	v_pk_mul_f32 v[166:167], v[72:73], v[166:167]
	v_pk_mul_f32 v[168:169], v[74:75], v[168:169]
	v_cvt_pk_bf16_f32 v150, v162, v163
	v_cvt_pk_bf16_f32 v151, v164, v165
	v_cvt_pk_bf16_f32 v152, v166, v167
	v_cvt_pk_bf16_f32 v153, v168, v169
	global_store_dwordx4 v[146:147], v[150:153], off
	s_mov_b32 s9, 0x84000
	v_add_co_u32_e32 v146, vcc, s9, v144
	s_nop 0
	v_addc_co_u32_e32 v147, vcc, 0, v145, vcc
	v_pk_mul_f32 v[162:163], v[100:101], v[170:171] op_sel_hi:[1,0]
	v_pk_mul_f32 v[164:165], v[102:103], v[170:171] op_sel_hi:[1,0]
	v_pk_mul_f32 v[166:167], v[68:69], v[170:171] op_sel_hi:[1,0]
	v_pk_mul_f32 v[168:169], v[70:71], v[170:171] op_sel_hi:[1,0]
	v_exp_f32_e32 v162, v162
	v_exp_f32_e32 v163, v163
	v_exp_f32_e32 v164, v164
	v_exp_f32_e32 v165, v165
	v_exp_f32_e32 v166, v166
	v_exp_f32_e32 v167, v167
	v_exp_f32_e32 v168, v168
	v_exp_f32_e32 v169, v169
	v_pk_add_f32 v[162:163], v[162:163], v[172:173] op_sel_hi:[1,0]
	v_pk_add_f32 v[164:165], v[164:165], v[172:173] op_sel_hi:[1,0]
	v_pk_add_f32 v[166:167], v[166:167], v[172:173] op_sel_hi:[1,0]
	v_pk_add_f32 v[168:169], v[168:169], v[172:173] op_sel_hi:[1,0]
	v_rcp_f32_e32 v162, v162
	v_rcp_f32_e32 v163, v163
	v_rcp_f32_e32 v164, v164
	v_rcp_f32_e32 v165, v165
	v_rcp_f32_e32 v166, v166
	v_rcp_f32_e32 v167, v167
	v_rcp_f32_e32 v168, v168
	v_rcp_f32_e32 v169, v169
	v_pk_mul_f32 v[162:163], v[100:101], v[162:163]
	v_pk_mul_f32 v[164:165], v[102:103], v[164:165]
	v_pk_mul_f32 v[166:167], v[68:69], v[166:167]
	v_pk_mul_f32 v[168:169], v[70:71], v[168:169]
	v_pk_mul_f32 v[162:163], v[96:97], v[162:163]
	v_pk_mul_f32 v[164:165], v[98:99], v[164:165]
	v_pk_mul_f32 v[166:167], v[64:65], v[166:167]
	v_pk_mul_f32 v[168:169], v[66:67], v[168:169]
	v_cvt_pk_bf16_f32 v150, v162, v163
	v_cvt_pk_bf16_f32 v151, v164, v165
	v_cvt_pk_bf16_f32 v152, v166, v167
	v_cvt_pk_bf16_f32 v153, v168, v169
	global_store_dwordx4 v[146:147], v[150:153], off
	v_mfma_f32_32x32x16_bf16 v[64:79], v[176:179], v[176:179], 0
	v_mfma_f32_32x32x16_bf16 v[96:111], v[176:179], v[176:179], 0
	s_mov_b32 s9, 0x160000
	v_add_co_u32_e32 v146, vcc, s9, v144
	s_nop 0
	v_addc_co_u32_e32 v147, vcc, 0, v145, vcc
	v_pk_mul_f32 v[162:163], v[60:61], v[170:171] op_sel_hi:[1,0]
	v_pk_mul_f32 v[164:165], v[62:63], v[170:171] op_sel_hi:[1,0]
	v_pk_mul_f32 v[166:167], v[28:29], v[170:171] op_sel_hi:[1,0]
	v_pk_mul_f32 v[168:169], v[30:31], v[170:171] op_sel_hi:[1,0]
	v_exp_f32_e32 v162, v162
	v_exp_f32_e32 v163, v163
	v_exp_f32_e32 v164, v164
	v_exp_f32_e32 v165, v165
	v_exp_f32_e32 v166, v166
	v_exp_f32_e32 v167, v167
	v_exp_f32_e32 v168, v168
	v_exp_f32_e32 v169, v169
	v_pk_add_f32 v[162:163], v[162:163], v[172:173] op_sel_hi:[1,0]
	v_pk_add_f32 v[164:165], v[164:165], v[172:173] op_sel_hi:[1,0]
	v_pk_add_f32 v[166:167], v[166:167], v[172:173] op_sel_hi:[1,0]
	v_pk_add_f32 v[168:169], v[168:169], v[172:173] op_sel_hi:[1,0]
	v_rcp_f32_e32 v162, v162
	v_rcp_f32_e32 v163, v163
	v_rcp_f32_e32 v164, v164
	v_rcp_f32_e32 v165, v165
	v_rcp_f32_e32 v166, v166
	v_rcp_f32_e32 v167, v167
	v_rcp_f32_e32 v168, v168
	v_rcp_f32_e32 v169, v169
	v_pk_mul_f32 v[162:163], v[60:61], v[162:163]
	v_pk_mul_f32 v[164:165], v[62:63], v[164:165]
	v_pk_mul_f32 v[166:167], v[28:29], v[166:167]
; __device__ __forceinline__ unsigned cvt_pk_bf16(float lo, float hi) { unsigned r; asm volatile("v_cvt_pk_bf16_f32 %0, %1, %2" : "=v"(r) : "v"(lo), "v"(hi)); return r; }
; template <class Epi>
; __device__ __forceinline__ void gemm_phase(LAS unsigned char* lds, const Gemm g, const Sched& S, const Epi& E) {
;     ...
;         if (!has_next) break;
; #pragma unroll
;         for (int a = 0; a < 2; ++a)
; #pragma unroll
;             for (int b = 0; b < 2; ++b)
; #pragma unroll
;                 for (int m = 0; m < 4; ++m)
; #pragma unroll
;                     for (int n = 0; n < 2; ++n) acc[a][b][m][n] = (f32x4){0.f, 0.f, 0.f, 0.f};
;         cur = nxt; cA = nA; cB = nB; ++ui;
;     __device__ __forceinline__ void operator()(AccRef acc, const Unit& u, int wr, int wc, int fr, int fq) const {
;     ...
;         for (int ai = 0; ai < 2; ++ai)
; #pragma unroll
;             for (int m = 0; m < 4; ++m) { const size_t row = (size_t)u.pm * 256 + ai * 128 + wr * 64 + m * 16 + fr; float o[8];
; #pragma unroll
;                 for (int bj = 0; bj < 2; ++bj) { const f32x4 gg = acc[ai][bj][m][0], uu = acc[ai][bj][m][1];
; #pragma unroll
;                     for (int j = 0; j < 4; ++j) o[4 * bj + j] = gg[j] * __builtin_amdgcn_rcpf(1.0f + __expf(-gg[j])) * uu[j]; }
;                 u32x4 w; w.x = cvt_pk_bf16(o[0], o[1]); w.y = cvt_pk_bf16(o[2], o[3]); w.z = cvt_pk_bf16(o[4], o[5]); w.w = cvt_pk_bf16(o[6], o[7]);
;                 *(u32x4*)(act + row * FF_ + (u.pn * 4 + wc) * 32 + 8 * fq) = w; }
	v_pk_mul_f32 v[168:169], v[30:31], v[168:169]
	v_pk_mul_f32 v[162:163], v[56:57], v[162:163]
	v_pk_mul_f32 v[164:165], v[58:59], v[164:165]
	v_pk_mul_f32 v[166:167], v[24:25], v[166:167]
	v_pk_mul_f32 v[168:169], v[26:27], v[168:169]
	v_cvt_pk_bf16_f32 v150, v162, v163
	v_cvt_pk_bf16_f32 v151, v164, v165
	v_cvt_pk_bf16_f32 v152, v166, v167
	v_cvt_pk_bf16_f32 v153, v168, v169
	global_store_dwordx4 v[146:147], v[150:153], off
	s_mov_b32 s9, 0x18c000
	v_add_co_u32_e32 v146, vcc, s9, v144
	s_nop 0
	v_addc_co_u32_e32 v147, vcc, 0, v145, vcc
	v_pk_mul_f32 v[162:163], v[52:53], v[170:171] op_sel_hi:[1,0]
	v_pk_mul_f32 v[164:165], v[54:55], v[170:171] op_sel_hi:[1,0]
	v_pk_mul_f32 v[166:167], v[20:21], v[170:171] op_sel_hi:[1,0]
	v_pk_mul_f32 v[168:169], v[22:23], v[170:171] op_sel_hi:[1,0]
	v_exp_f32_e32 v162, v162
	v_exp_f32_e32 v163, v163
	v_exp_f32_e32 v164, v164
	v_exp_f32_e32 v165, v165
	v_exp_f32_e32 v166, v166
	v_exp_f32_e32 v167, v167
	v_exp_f32_e32 v168, v168
	v_exp_f32_e32 v169, v169
	v_pk_add_f32 v[162:163], v[162:163], v[172:173] op_sel_hi:[1,0]
	v_pk_add_f32 v[164:165], v[164:165], v[172:173] op_sel_hi:[1,0]
	v_pk_add_f32 v[166:167], v[166:167], v[172:173] op_sel_hi:[1,0]
	v_pk_add_f32 v[168:169], v[168:169], v[172:173] op_sel_hi:[1,0]
	v_rcp_f32_e32 v162, v162
	v_rcp_f32_e32 v163, v163
	v_rcp_f32_e32 v164, v164
	v_rcp_f32_e32 v165, v165
	v_rcp_f32_e32 v166, v166
	v_rcp_f32_e32 v167, v167
	v_rcp_f32_e32 v168, v168
	v_rcp_f32_e32 v169, v169
	v_pk_mul_f32 v[162:163], v[52:53], v[162:163]
	v_pk_mul_f32 v[164:165], v[54:55], v[164:165]
	v_pk_mul_f32 v[166:167], v[20:21], v[166:167]
	v_pk_mul_f32 v[168:169], v[22:23], v[168:169]
	v_pk_mul_f32 v[162:163], v[48:49], v[162:163]
	v_pk_mul_f32 v[164:165], v[50:51], v[164:165]
	v_pk_mul_f32 v[166:167], v[16:17], v[166:167]
	v_pk_mul_f32 v[168:169], v[18:19], v[168:169]
	v_cvt_pk_bf16_f32 v150, v162, v163
	v_cvt_pk_bf16_f32 v151, v164, v165
	v_cvt_pk_bf16_f32 v152, v166, v167
	v_cvt_pk_bf16_f32 v153, v168, v169
	global_store_dwordx4 v[146:147], v[150:153], off
	v_mfma_f32_32x32x16_bf16 v[16:31], v[176:179], v[176:179], 0
	v_mfma_f32_32x32x16_bf16 v[48:63], v[176:179], v[176:179], 0
	v_add_co_u32_e32 v146, vcc, s65, v144
	s_nop 0
	v_addc_co_u32_e32 v147, vcc, 0, v145, vcc
	v_pk_mul_f32 v[162:163], v[44:45], v[170:171] op_sel_hi:[1,0]
	v_pk_mul_f32 v[164:165], v[46:47], v[170:171] op_sel_hi:[1,0]
	v_pk_mul_f32 v[166:167], v[12:13], v[170:171] op_sel_hi:[1,0]
	v_pk_mul_f32 v[168:169], v[14:15], v[170:171] op_sel_hi:[1,0]
	v_exp_f32_e32 v162, v162
	v_exp_f32_e32 v163, v163
	v_exp_f32_e32 v164, v164
	v_exp_f32_e32 v165, v165
	v_exp_f32_e32 v166, v166
	v_exp_f32_e32 v167, v167
	v_exp_f32_e32 v168, v168
	v_exp_f32_e32 v169, v169
	v_pk_add_f32 v[162:163], v[162:163], v[172:173] op_sel_hi:[1,0]
	v_pk_add_f32 v[164:165], v[164:165], v[172:173] op_sel_hi:[1,0]
	v_pk_add_f32 v[166:167], v[166:167], v[172:173] op_sel_hi:[1,0]
	v_pk_add_f32 v[168:169], v[168:169], v[172:173] op_sel_hi:[1,0]
	v_rcp_f32_e32 v162, v162
	v_rcp_f32_e32 v163, v163
	v_rcp_f32_e32 v164, v164
	v_rcp_f32_e32 v165, v165
	v_rcp_f32_e32 v166, v166
	v_rcp_f32_e32 v167, v167
	v_rcp_f32_e32 v168, v168
	v_rcp_f32_e32 v169, v169
	v_pk_mul_f32 v[162:163], v[44:45], v[162:163]
	v_pk_mul_f32 v[164:165], v[46:47], v[164:165]
	v_pk_mul_f32 v[166:167], v[12:13], v[166:167]
	v_pk_mul_f32 v[168:169], v[14:15], v[168:169]
	v_pk_mul_f32 v[162:163], v[40:41], v[162:163]
	v_pk_mul_f32 v[164:165], v[42:43], v[164:165]
	v_pk_mul_f32 v[166:167], v[8:9], v[166:167]
	v_pk_mul_f32 v[168:169], v[10:11], v[168:169]
	v_cvt_pk_bf16_f32 v150, v162, v163
	v_cvt_pk_bf16_f32 v151, v164, v165
	v_cvt_pk_bf16_f32 v152, v166, v167
	v_cvt_pk_bf16_f32 v153, v168, v169
	global_store_dwordx4 v[146:147], v[150:153], off
	v_add_co_u32_e32 v144, vcc, 0x1e4000, v144
	v_addc_co_u32_e32 v145, vcc, 0, v145, vcc
	s_andn2_b64 vcc, exec, s[6:7]
	v_pk_mul_f32 v[162:163], v[36:37], v[170:171] op_sel_hi:[1,0]
	v_pk_mul_f32 v[164:165], v[38:39], v[170:171] op_sel_hi:[1,0]
	v_pk_mul_f32 v[166:167], v[4:5], v[170:171] op_sel_hi:[1,0]
	v_pk_mul_f32 v[168:169], v[6:7], v[170:171] op_sel_hi:[1,0]
	v_exp_f32_e32 v162, v162
	v_exp_f32_e32 v163, v163
	v_exp_f32_e32 v164, v164
	v_exp_f32_e32 v165, v165
	v_exp_f32_e32 v166, v166
	v_exp_f32_e32 v167, v167
	v_exp_f32_e32 v168, v168
	v_exp_f32_e32 v169, v169
	v_pk_add_f32 v[162:163], v[162:163], v[172:173] op_sel_hi:[1,0]
	v_pk_add_f32 v[164:165], v[164:165], v[172:173] op_sel_hi:[1,0]
	v_pk_add_f32 v[166:167], v[166:167], v[172:173] op_sel_hi:[1,0]
	v_pk_add_f32 v[168:169], v[168:169], v[172:173] op_sel_hi:[1,0]
	v_rcp_f32_e32 v162, v162
	v_rcp_f32_e32 v163, v163
	v_rcp_f32_e32 v164, v164
	v_rcp_f32_e32 v165, v165
	v_rcp_f32_e32 v166, v166
	v_rcp_f32_e32 v167, v167
	v_rcp_f32_e32 v168, v168
	v_rcp_f32_e32 v169, v169
	v_pk_mul_f32 v[162:163], v[36:37], v[162:163]
	v_pk_mul_f32 v[164:165], v[38:39], v[164:165]
	v_pk_mul_f32 v[166:167], v[4:5], v[166:167]
	v_pk_mul_f32 v[168:169], v[6:7], v[168:169]
	v_pk_mul_f32 v[162:163], v[32:33], v[162:163]
	v_pk_mul_f32 v[164:165], v[34:35], v[164:165]
	v_pk_mul_f32 v[166:167], v[0:1], v[166:167]
	v_pk_mul_f32 v[168:169], v[2:3], v[168:169]
	v_cvt_pk_bf16_f32 v150, v162, v163
	v_cvt_pk_bf16_f32 v151, v164, v165
	v_cvt_pk_bf16_f32 v152, v166, v167
	v_cvt_pk_bf16_f32 v153, v168, v169
	global_store_dwordx4 v[144:145], v[150:153], off
	v_mfma_f32_32x32x16_bf16 v[0:15], v[176:179], v[176:179], 0
	v_mfma_f32_32x32x16_bf16 v[32:47], v[176:179], v[176:179], 0
	s_cbranch_vccz .LBB0_173
	s_mov_b64 s[20:21], s[24:25]
	s_andn2_b64 vcc, exec, s[4:5]
	s_mov_b64 s[24:25], s[20:21]
	s_cbranch_vccnz .LBB0_174

; #define PG8_STAGE(bufoff, gbase, voff) do { _Pragma("unroll") for (int _i = 0; _i < 2; ++_i) \
;         __builtin_amdgcn_global_load_lds((const unsigned*)((const char*)(gbase) + (voff)[_i]), (LAS unsigned*)(lds + (bufoff) + ldsw + _i * 8192), 16, 0, 0); } while (0)
; #define PG8_LDA(dst, b, h) do { _Pragma("unroll") for (int m = 0; m < 4; ++m) _Pragma("unroll") for (int k = 0; k < 2; ++k) dst[m][k] = *(const LAS bf16x8*)(lds + PG8_SA(b, h) + aoff + m * 2048 + k * 1024); } while (0)
; #define PG8_LDB(dst, b, h) do { _Pragma("unroll") for (int n = 0; n < 2; ++n) _Pragma("unroll") for (int k = 0; k < 2; ++k) dst[n][k] = *(const LAS bf16x8*)(lds + PG8_SB(b, h) + boff + n * 2048 + k * 1024); } while (0)
; #define PG8_MMA(ai, bj, At, Bt) do { __builtin_amdgcn_s_setprio(1); _Pragma("unroll") for (int m = 0; m < 4; ++m) _Pragma("unroll") for (int n = 0; n < 2; ++n) _Pragma("unroll") for (int k = 0; k < 2; ++k) \
;         acc[ai][bj][m][n] = __builtin_amdgcn_mfma_f32_16x16x32_bf16(Bt[n][k], At[m][k], acc[ai][bj][m][n], 0, 0, 0); __builtin_amdgcn_s_setprio(0); } while (0)
; #define PG8_WAIT_L(n) asm volatile("s_waitcnt lgkmcnt(" #n ")" ::: "memory")
; #define PG8_BAR __builtin_amdgcn_s_barrier()
; #define PG8_SCHED __builtin_amdgcn_sched_barrier(0)
; template <class Epi>
; __device__ __forceinline__ void gemm_phase(LAS unsigned char* lds, const Gemm g, const Sched& S, const Epi& E) {
;     ...
;             PG8_LDB(B0, 0, 0); PG8_SCHED; PG8_LDA(At, 0, 0); PG8_STAGE(PG8_SA(1, 1), a1 + hstepA, voffA);
;             PG8_WAIT_L(8); PG8_BAR; PG8_WAIT_L(0); PG8_MMA(0, 0, At, B0); PG8_BAR; PG8_SCHED;
;             PG8_LDB(B1, 0, 1); PG8_STAGE(PG8_SB(0, 0), b2, voffB);
;             PG8_BAR; PG8_WAIT_L(0); PG8_MMA(0, 1, At, B1); PG8_BAR;
;             PG8_LDA(At, 0, 1); PG8_STAGE(PG8_SA(0, 0), a2, voffA);
;             PG8_BAR; PG8_WAIT_L(0); PG8_MMA(1, 0, At, B0); PG8_BAR; PG8_SCHED;
.LBB0_2088:
	v_add_u32_e32 v162, s62, v148
	s_add_u32 s38, s14, s36
	ds_read_b128 v[150:153], v162
	ds_read_b128 v[154:157], v162 offset:1024
	ds_read_b128 v[158:161], v162 offset:2048
	ds_read_b128 v[162:165], v162 offset:3072
	s_addc_u32 s39, s15, s37
	s_add_u32 s38, s38, 0x100
	s_addc_u32 s39, s39, 0
	s_add_u32 s82, s13, s36
	s_addc_u32 s83, s51, s37
	s_cmpk_eq_i32 s36, 0xf00
	s_cselect_b32 s55, s21, s39
	s_cselect_b32 s54, s79, s38
	s_cselect_b32 s39, s19, s83
	s_cselect_b32 s38, s80, s82
	v_lshl_add_u64 v[190:191], v[144:145], 0, s[36:37]
	s_add_i32 m0, s43, 0xc000
	ds_read_b128 v[166:169], v149
	ds_read_b128 v[170:173], v149 offset:1024
	ds_read_b128 v[174:177], v149 offset:2048
	ds_read_b128 v[178:181], v149 offset:3072
	ds_read_b128 v[182:185], v149 offset:4096
	ds_read_b128 v[186:189], v149 offset:5120
	ds_read_b128 v[194:197], v149 offset:6144
	ds_read_b128 v[198:201], v149 offset:7168
	global_load_lds_dwordx4 v[190:191], off
	v_lshl_add_u64 v[190:191], v[146:147], 0, s[36:37]
	s_add_i32 m0, s43, 0xe000
	s_nop 0
	global_load_lds_dwordx4 v[190:191], off
	s_waitcnt lgkmcnt(8)
	s_barrier
	s_waitcnt lgkmcnt(0)
	s_setprio 1
	s_waitcnt lgkmcnt(0)
	v_mfma_f32_16x16x32_bf16 v[124:127], v[150:153], v[166:169], v[124:127]
	v_mfma_f32_16x16x32_bf16 v[120:123], v[158:161], v[166:169], v[120:123]
	v_mfma_f32_16x16x32_bf16 v[116:119], v[150:153], v[174:177], v[116:119]
	v_mfma_f32_16x16x32_bf16 v[112:115], v[158:161], v[174:177], v[112:115]
	v_mfma_f32_16x16x32_bf16 v[108:111], v[150:153], v[182:185], v[108:111]
	v_mfma_f32_16x16x32_bf16 v[104:107], v[158:161], v[182:185], v[104:107]
	v_mfma_f32_16x16x32_bf16 v[100:103], v[150:153], v[194:197], v[100:103]
	v_mfma_f32_16x16x32_bf16 v[96:99], v[158:161], v[194:197], v[96:99]
	v_mfma_f32_16x16x32_bf16 v[124:127], v[154:157], v[170:173], v[124:127]
	v_mfma_f32_16x16x32_bf16 v[120:123], v[162:165], v[170:173], v[120:123]
	v_mfma_f32_16x16x32_bf16 v[116:119], v[154:157], v[178:181], v[116:119]
	v_mfma_f32_16x16x32_bf16 v[112:115], v[162:165], v[178:181], v[112:115]
	v_mfma_f32_16x16x32_bf16 v[108:111], v[154:157], v[186:189], v[108:111]
	v_mfma_f32_16x16x32_bf16 v[104:107], v[162:165], v[186:189], v[104:107]
	v_mfma_f32_16x16x32_bf16 v[100:103], v[154:157], v[198:201], v[100:103]
	v_mfma_f32_16x16x32_bf16 v[96:99], v[162:165], v[198:201], v[96:99]
	s_setprio 0
	s_barrier
	v_add_u32_e32 v190, s63, v148
	s_add_i32 s82, s62, s34
	ds_read_b128 v[202:205], v190
	ds_read_b128 v[206:209], v190 offset:1024
	ds_read_b128 v[210:213], v190 offset:2048
	ds_read_b128 v[214:217], v190 offset:3072
	v_lshl_add_u64 v[190:191], s[38:39], 0, v[130:131]
	s_mov_b32 m0, s82
	v_lshl_add_u64 v[218:219], s[38:39], 0, v[128:129]
	global_load_lds_dwordx4 v[190:191], off
	s_add_i32 m0, s82, 0x2000
	s_nop 0
	global_load_lds_dwordx4 v[218:219], off
	s_barrier
	s_waitcnt lgkmcnt(0)
	s_setprio 1
	s_waitcnt lgkmcnt(0)
	v_mfma_f32_16x16x32_bf16 v[92:95], v[202:205], v[166:169], v[92:95]
	v_mfma_f32_16x16x32_bf16 v[88:91], v[210:213], v[166:169], v[88:91]
	v_mfma_f32_16x16x32_bf16 v[84:87], v[202:205], v[174:177], v[84:87]
	v_mfma_f32_16x16x32_bf16 v[80:83], v[210:213], v[174:177], v[80:83]
	v_mfma_f32_16x16x32_bf16 v[76:79], v[202:205], v[182:185], v[76:79]
	v_mfma_f32_16x16x32_bf16 v[72:75], v[210:213], v[182:185], v[72:75]
	v_mfma_f32_16x16x32_bf16 v[68:71], v[202:205], v[194:197], v[68:71]
	v_mfma_f32_16x16x32_bf16 v[64:67], v[210:213], v[194:197], v[64:67]
	v_mfma_f32_16x16x32_bf16 v[92:95], v[206:209], v[170:173], v[92:95]
	v_mfma_f32_16x16x32_bf16 v[88:91], v[214:217], v[170:173], v[88:91]
	v_mfma_f32_16x16x32_bf16 v[84:87], v[206:209], v[178:181], v[84:87]
	v_mfma_f32_16x16x32_bf16 v[80:83], v[214:217], v[178:181], v[80:83]
	v_mfma_f32_16x16x32_bf16 v[76:79], v[206:209], v[186:189], v[76:79]
	v_mfma_f32_16x16x32_bf16 v[72:75], v[214:217], v[186:189], v[72:75]
	v_mfma_f32_16x16x32_bf16 v[68:71], v[206:209], v[198:201], v[68:71]
	v_mfma_f32_16x16x32_bf16 v[64:67], v[214:217], v[198:201], v[64:67]
	s_setprio 0
	s_mov_b32 m0, s43
	v_lshl_add_u64 v[220:221], s[54:55], 0, v[130:131]
	s_barrier
	ds_read_b128 v[166:169], v149 offset:16384
	ds_read_b128 v[170:173], v149 offset:17408
	ds_read_b128 v[174:177], v149 offset:18432
	ds_read_b128 v[178:181], v149 offset:19456
	ds_read_b128 v[182:185], v149 offset:20480
	ds_read_b128 v[186:189], v149 offset:21504
	ds_read_b128 v[194:197], v149 offset:22528
	ds_read_b128 v[198:201], v149 offset:23552
	global_load_lds_dwordx4 v[220:221], off
	v_lshl_add_u64 v[222:223], s[54:55], 0, v[128:129]
	s_mov_b32 m0, s52
	s_nop 0
	global_load_lds_dwordx4 v[222:223], off
	s_barrier
	s_waitcnt lgkmcnt(0)
	s_setprio 1
	s_waitcnt lgkmcnt(0)
	v_mfma_f32_16x16x32_bf16 v[60:63], v[150:153], v[166:169], v[60:63]
	v_mfma_f32_16x16x32_bf16 v[56:59], v[158:161], v[166:169], v[56:59]
	v_mfma_f32_16x16x32_bf16 v[52:55], v[150:153], v[174:177], v[52:55]
	v_mfma_f32_16x16x32_bf16 v[48:51], v[158:161], v[174:177], v[48:51]
	v_mfma_f32_16x16x32_bf16 v[44:47], v[150:153], v[182:185], v[44:47]
	v_mfma_f32_16x16x32_bf16 v[40:43], v[158:161], v[182:185], v[40:43]
	v_mfma_f32_16x16x32_bf16 v[36:39], v[150:153], v[194:197], v[36:39]
	v_mfma_f32_16x16x32_bf16 v[32:35], v[158:161], v[194:197], v[32:35]
	v_mfma_f32_16x16x32_bf16 v[60:63], v[154:157], v[170:173], v[60:63]
	v_mfma_f32_16x16x32_bf16 v[56:59], v[162:165], v[170:173], v[56:59]
	v_mfma_f32_16x16x32_bf16 v[52:55], v[154:157], v[178:181], v[52:55]
	v_mfma_f32_16x16x32_bf16 v[48:51], v[162:165], v[178:181], v[48:51]
	v_mfma_f32_16x16x32_bf16 v[44:47], v[154:157], v[186:189], v[44:47]
	v_mfma_f32_16x16x32_bf16 v[40:43], v[162:165], v[186:189], v[40:43]
	v_mfma_f32_16x16x32_bf16 v[36:39], v[154:157], v[198:201], v[36:39]
	v_mfma_f32_16x16x32_bf16 v[32:35], v[162:165], v[198:201], v[32:35]
	s_setprio 0
	s_barrier
; #define PG8_STAGE(bufoff, gbase, voff) do { _Pragma("unroll") for (int _i = 0; _i < 2; ++_i) \
;         __builtin_amdgcn_global_load_lds((const unsigned*)((const char*)(gbase) + (voff)[_i]), (LAS unsigned*)(lds + (bufoff) + ldsw + _i * 8192), 16, 0, 0); } while (0)
; #define PG8_LDA(dst, b, h) do { _Pragma("unroll") for (int m = 0; m < 4; ++m) _Pragma("unroll") for (int k = 0; k < 2; ++k) dst[m][k] = *(const LAS bf16x8*)(lds + PG8_SA(b, h) + aoff + m * 2048 + k * 1024); } while (0)
; #define PG8_LDB(dst, b, h) do { _Pragma("unroll") for (int n = 0; n < 2; ++n) _Pragma("unroll") for (int k = 0; k < 2; ++k) dst[n][k] = *(const LAS bf16x8*)(lds + PG8_SB(b, h) + boff + n * 2048 + k * 1024); } while (0)
; #define PG8_MMA(ai, bj, At, Bt) do { __builtin_amdgcn_s_setprio(1); _Pragma("unroll") for (int m = 0; m < 4; ++m) _Pragma("unroll") for (int n = 0; n < 2; ++n) _Pragma("unroll") for (int k = 0; k < 2; ++k) \
;         acc[ai][bj][m][n] = __builtin_amdgcn_mfma_f32_16x16x32_bf16(Bt[n][k], At[m][k], acc[ai][bj][m][n], 0, 0, 0); __builtin_amdgcn_s_setprio(0); } while (0)
; #define PG8_WAIT_V(n) asm volatile("s_waitcnt vmcnt(" #n ")" ::: "memory")
; #define PG8_WAIT_L(n) asm volatile("s_waitcnt lgkmcnt(" #n ")" ::: "memory")
; #define PG8_BAR __builtin_amdgcn_s_barrier()
; #define PG8_SCHED __builtin_amdgcn_sched_barrier(0)
; template <class Epi>
; __device__ __forceinline__ void gemm_phase(LAS unsigned char* lds, const Gemm g, const Sched& S, const Epi& E) {
;     ...
;             PG8_STAGE(PG8_SB(0, 1), b2 + hstepB, voffB);
;             PG8_WAIT_V(6); PG8_BAR; PG8_MMA(1, 1, At, B1); PG8_BAR;
;             PG8_LDB(B0, 1, 0); PG8_SCHED; PG8_LDA(At, 1, 0); PG8_STAGE(PG8_SA(0, 1), a2 + hstepA, voffA);
;             PG8_WAIT_L(8); PG8_BAR; PG8_WAIT_L(0); PG8_MMA(0, 0, At, B0); PG8_BAR; PG8_SCHED;
;             PG8_LDB(B1, 1, 1); PG8_STAGE(PG8_SB(1, 0), b3, voffB);
;             PG8_BAR; PG8_WAIT_L(0); PG8_MMA(0, 1, At, B1); PG8_BAR;
;             PG8_LDA(At, 1, 1); PG8_STAGE(PG8_SA(1, 0), a3, voffA);
	s_add_u32 s82, s38, 0x80000
	s_addc_u32 s83, s39, 0
	s_add_i32 s84, s63, s34
	v_lshl_add_u64 v[150:151], s[82:83], 0, v[130:131]
	s_mov_b32 m0, s84
	s_nop 0
	global_load_lds_dwordx4 v[150:151], off
	v_lshl_add_u64 v[150:151], s[82:83], 0, v[128:129]
	s_add_i32 m0, s84, 0x2000
	s_nop 0
	global_load_lds_dwordx4 v[150:151], off
	s_waitcnt vmcnt(6)
	s_barrier
	s_setprio 1
	v_mfma_f32_16x16x32_bf16 v[28:31], v[202:205], v[166:169], v[28:31]
	v_mfma_f32_16x16x32_bf16 v[24:27], v[210:213], v[166:169], v[24:27]
	v_mfma_f32_16x16x32_bf16 v[20:23], v[202:205], v[174:177], v[20:23]
	v_mfma_f32_16x16x32_bf16 v[16:19], v[210:213], v[174:177], v[16:19]
	v_mfma_f32_16x16x32_bf16 v[12:15], v[202:205], v[182:185], v[12:15]
	v_mfma_f32_16x16x32_bf16 v[8:11], v[210:213], v[182:185], v[8:11]
	v_mfma_f32_16x16x32_bf16 v[4:7], v[202:205], v[194:197], v[4:7]
	v_mfma_f32_16x16x32_bf16 v[0:3], v[210:213], v[194:197], v[0:3]
	v_mfma_f32_16x16x32_bf16 v[28:31], v[206:209], v[170:173], v[28:31]
	v_mfma_f32_16x16x32_bf16 v[24:27], v[214:217], v[170:173], v[24:27]
	v_mfma_f32_16x16x32_bf16 v[20:23], v[206:209], v[178:181], v[20:23]
	v_mfma_f32_16x16x32_bf16 v[16:19], v[214:217], v[178:181], v[16:19]
	v_mfma_f32_16x16x32_bf16 v[12:15], v[206:209], v[186:189], v[12:15]
	v_mfma_f32_16x16x32_bf16 v[8:11], v[214:217], v[186:189], v[8:11]
	v_mfma_f32_16x16x32_bf16 v[4:7], v[206:209], v[198:201], v[4:7]
	v_mfma_f32_16x16x32_bf16 v[0:3], v[214:217], v[198:201], v[0:3]
	s_setprio 0
	s_add_i32 s82, 0, 0x18000
	v_add_u32_e32 v162, s82, v148
	s_barrier
	ds_read_b128 v[150:153], v162
	ds_read_b128 v[154:157], v162 offset:1024
	ds_read_b128 v[158:161], v162 offset:2048
	ds_read_b128 v[162:165], v162 offset:3072
	s_add_u32 s54, s54, 0x80000
	s_addc_u32 s55, s55, 0
	s_mov_b32 m0, s53
	v_lshl_add_u64 v[202:203], s[54:55], 0, v[130:131]
	ds_read_b128 v[166:169], v149 offset:32768
	ds_read_b128 v[170:173], v149 offset:33792
	ds_read_b128 v[174:177], v149 offset:34816
	ds_read_b128 v[178:181], v149 offset:35840
	ds_read_b128 v[182:185], v149 offset:36864
	ds_read_b128 v[186:189], v149 offset:37888
	ds_read_b128 v[194:197], v149 offset:38912
	ds_read_b128 v[198:201], v149 offset:39936
	global_load_lds_dwordx4 v[202:203], off
	v_lshl_add_u64 v[202:203], s[54:55], 0, v[128:129]
	s_mov_b32 m0, s56
	s_nop 0
	global_load_lds_dwordx4 v[202:203], off
	s_waitcnt lgkmcnt(8)
	s_barrier
	s_waitcnt lgkmcnt(0)
	s_setprio 1
	s_waitcnt lgkmcnt(0)
	v_mfma_f32_16x16x32_bf16 v[124:127], v[150:153], v[166:169], v[124:127]
	v_mfma_f32_16x16x32_bf16 v[120:123], v[158:161], v[166:169], v[120:123]
	v_mfma_f32_16x16x32_bf16 v[116:119], v[150:153], v[174:177], v[116:119]
	v_mfma_f32_16x16x32_bf16 v[112:115], v[158:161], v[174:177], v[112:115]
	v_mfma_f32_16x16x32_bf16 v[108:111], v[150:153], v[182:185], v[108:111]
	v_mfma_f32_16x16x32_bf16 v[104:107], v[158:161], v[182:185], v[104:107]
	v_mfma_f32_16x16x32_bf16 v[100:103], v[150:153], v[194:197], v[100:103]
	v_mfma_f32_16x16x32_bf16 v[96:99], v[158:161], v[194:197], v[96:99]
	v_mfma_f32_16x16x32_bf16 v[124:127], v[154:157], v[170:173], v[124:127]
	v_mfma_f32_16x16x32_bf16 v[120:123], v[162:165], v[170:173], v[120:123]
	v_mfma_f32_16x16x32_bf16 v[116:119], v[154:157], v[178:181], v[116:119]
	v_mfma_f32_16x16x32_bf16 v[112:115], v[162:165], v[178:181], v[112:115]
	v_mfma_f32_16x16x32_bf16 v[108:111], v[154:157], v[186:189], v[108:111]
	v_mfma_f32_16x16x32_bf16 v[104:107], v[162:165], v[186:189], v[104:107]
	v_mfma_f32_16x16x32_bf16 v[100:103], v[154:157], v[198:201], v[100:103]
	v_mfma_f32_16x16x32_bf16 v[96:99], v[162:165], v[198:201], v[96:99]
	s_setprio 0
	s_barrier
	s_add_i32 s54, 0, 0x1c000
	s_add_i32 s55, s82, s34
	v_add_u32_e32 v214, s54, v148
	v_lshl_add_u64 v[190:191], v[190:191], 0, s[16:17]
	s_mov_b32 m0, s55
	ds_read_b128 v[202:205], v214
	ds_read_b128 v[206:209], v214 offset:1024
	ds_read_b128 v[210:213], v214 offset:2048
	ds_read_b128 v[214:217], v214 offset:3072
	global_load_lds_dwordx4 v[190:191], off
	v_lshl_add_u64 v[190:191], v[218:219], 0, s[16:17]
	s_add_i32 m0, s55, 0x2000
	s_nop 0
	global_load_lds_dwordx4 v[190:191], off
	s_barrier
	s_waitcnt lgkmcnt(0)
	s_setprio 1
	s_waitcnt lgkmcnt(0)
	v_mfma_f32_16x16x32_bf16 v[92:95], v[202:205], v[166:169], v[92:95]
	v_mfma_f32_16x16x32_bf16 v[88:91], v[210:213], v[166:169], v[88:91]
	v_mfma_f32_16x16x32_bf16 v[84:87], v[202:205], v[174:177], v[84:87]
	v_mfma_f32_16x16x32_bf16 v[80:83], v[210:213], v[174:177], v[80:83]
	v_mfma_f32_16x16x32_bf16 v[76:79], v[202:205], v[182:185], v[76:79]
	v_mfma_f32_16x16x32_bf16 v[72:75], v[210:213], v[182:185], v[72:75]
	v_mfma_f32_16x16x32_bf16 v[68:71], v[202:205], v[194:197], v[68:71]
	v_mfma_f32_16x16x32_bf16 v[64:67], v[210:213], v[194:197], v[64:67]
	v_mfma_f32_16x16x32_bf16 v[92:95], v[206:209], v[170:173], v[92:95]
	v_mfma_f32_16x16x32_bf16 v[88:91], v[214:217], v[170:173], v[88:91]
	v_mfma_f32_16x16x32_bf16 v[84:87], v[206:209], v[178:181], v[84:87]
	v_mfma_f32_16x16x32_bf16 v[80:83], v[214:217], v[178:181], v[80:83]
	v_mfma_f32_16x16x32_bf16 v[76:79], v[206:209], v[186:189], v[76:79]
	v_mfma_f32_16x16x32_bf16 v[72:75], v[214:217], v[186:189], v[72:75]
	v_mfma_f32_16x16x32_bf16 v[68:71], v[206:209], v[198:201], v[68:71]
	v_mfma_f32_16x16x32_bf16 v[64:67], v[214:217], v[198:201], v[64:67]
	s_setprio 0
	s_mov_b32 m0, s60
	v_lshl_add_u64 v[190:191], v[220:221], 0, s[16:17]
	s_barrier
	ds_read_b128 v[166:169], v149 offset:49152
	ds_read_b128 v[170:173], v149 offset:50176
	ds_read_b128 v[174:177], v149 offset:51200
	ds_read_b128 v[178:181], v149 offset:52224
	ds_read_b128 v[182:185], v149 offset:53248
	ds_read_b128 v[186:189], v149 offset:54272
	ds_read_b128 v[194:197], v149 offset:55296
	ds_read_b128 v[198:201], v149 offset:56320
	global_load_lds_dwordx4 v[190:191], off
	v_lshl_add_u64 v[190:191], v[222:223], 0, s[16:17]
	s_mov_b32 m0, s61
	s_nop 0
	global_load_lds_dwordx4 v[190:191], off
	s_barrier
; __device__ __forceinline__ unsigned cvt_pk_bf16(float lo, float hi) { unsigned r; asm volatile("v_cvt_pk_bf16_f32 %0, %1, %2" : "=v"(r) : "v"(lo), "v"(hi)); return r; }
; #define PG8_STAGE(bufoff, gbase, voff) do { _Pragma("unroll") for (int _i = 0; _i < 2; ++_i) \
;         __builtin_amdgcn_global_load_lds((const unsigned*)((const char*)(gbase) + (voff)[_i]), (LAS unsigned*)(lds + (bufoff) + ldsw + _i * 8192), 16, 0, 0); } while (0)
; #define PG8_MMA(ai, bj, At, Bt) do { __builtin_amdgcn_s_setprio(1); _Pragma("unroll") for (int m = 0; m < 4; ++m) _Pragma("unroll") for (int n = 0; n < 2; ++n) _Pragma("unroll") for (int k = 0; k < 2; ++k) \
;         acc[ai][bj][m][n] = __builtin_amdgcn_mfma_f32_16x16x32_bf16(Bt[n][k], At[m][k], acc[ai][bj][m][n], 0, 0, 0); __builtin_amdgcn_s_setprio(0); } while (0)
; #define PG8_WAIT_V(n) asm volatile("s_waitcnt vmcnt(" #n ")" ::: "memory")
; #define PG8_WAIT_L(n) asm volatile("s_waitcnt lgkmcnt(" #n ")" ::: "memory")
; #define PG8_BAR __builtin_amdgcn_s_barrier()
; #define PG8_SCHED __builtin_amdgcn_sched_barrier(0)
; template <class Epi>
; __device__ __forceinline__ void gemm_phase(LAS unsigned char* lds, const Gemm g, const Sched& S, const Epi& E) {
;     ...
;             PG8_BAR; PG8_WAIT_L(0); PG8_MMA(1, 0, At, B0); PG8_BAR; PG8_SCHED;
;             PG8_STAGE(PG8_SB(1, 1), b3 + hstepB, voffB);
;             PG8_WAIT_V(6); PG8_BAR; PG8_MMA(1, 1, At, B1); PG8_BAR;
;     __device__ __forceinline__ void operator()(AccRef acc, const Unit& u, int wr, int wc, int fr, int fq) const {
;     ...
;         for (int ai = 0; ai < 2; ++ai)
; #pragma unroll
;             for (int m = 0; m < 4; ++m) { const size_t row = (size_t)u.pm * 256 + ai * 128 + wr * 64 + m * 16 + fr; float o[8];
; #pragma unroll
;                 for (int bj = 0; bj < 2; ++bj) { const f32x4 gg = acc[ai][bj][m][0], uu = acc[ai][bj][m][1];
; #pragma unroll
;                     for (int j = 0; j < 4; ++j) o[4 * bj + j] = gg[j] * __builtin_amdgcn_rcpf(1.0f + __expf(-gg[j])) * uu[j]; }
;                 u32x4 w; w.x = cvt_pk_bf16(o[0], o[1]); w.y = cvt_pk_bf16(o[2], o[3]); w.z = cvt_pk_bf16(o[4], o[5]); w.w = cvt_pk_bf16(o[6], o[7]);
;                 *(u32x4*)(act + row * FF_ + (u.pn * 4 + wc) * 32 + 8 * fq) = w; }
	s_waitcnt lgkmcnt(0)
	s_setprio 1
	s_waitcnt lgkmcnt(0)
	v_mfma_f32_16x16x32_bf16 v[60:63], v[150:153], v[166:169], v[60:63]
	v_mfma_f32_16x16x32_bf16 v[56:59], v[158:161], v[166:169], v[56:59]
	v_mfma_f32_16x16x32_bf16 v[52:55], v[150:153], v[174:177], v[52:55]
	v_mfma_f32_16x16x32_bf16 v[48:51], v[158:161], v[174:177], v[48:51]
	v_mfma_f32_16x16x32_bf16 v[44:47], v[150:153], v[182:185], v[44:47]
	v_mfma_f32_16x16x32_bf16 v[40:43], v[158:161], v[182:185], v[40:43]
	v_mfma_f32_16x16x32_bf16 v[36:39], v[150:153], v[194:197], v[36:39]
	v_mfma_f32_16x16x32_bf16 v[32:35], v[158:161], v[194:197], v[32:35]
	v_mfma_f32_16x16x32_bf16 v[60:63], v[154:157], v[170:173], v[60:63]
	v_mfma_f32_16x16x32_bf16 v[56:59], v[162:165], v[170:173], v[56:59]
	v_mfma_f32_16x16x32_bf16 v[52:55], v[154:157], v[178:181], v[52:55]
	v_mfma_f32_16x16x32_bf16 v[48:51], v[162:165], v[178:181], v[48:51]
	v_mfma_f32_16x16x32_bf16 v[44:47], v[154:157], v[186:189], v[44:47]
	v_mfma_f32_16x16x32_bf16 v[40:43], v[162:165], v[186:189], v[40:43]
	v_mfma_f32_16x16x32_bf16 v[36:39], v[154:157], v[198:201], v[36:39]
	v_mfma_f32_16x16x32_bf16 v[32:35], v[162:165], v[198:201], v[32:35]
	s_setprio 0
	s_barrier
	s_add_u32 s38, s38, 0x80080
	s_addc_u32 s39, s39, 0
	s_add_i32 s54, s54, s34
	v_lshl_add_u64 v[150:151], s[38:39], 0, v[130:131]
	s_mov_b32 m0, s54
	s_nop 0
	global_load_lds_dwordx4 v[150:151], off
	v_lshl_add_u64 v[150:151], s[38:39], 0, v[128:129]
	s_add_i32 m0, s54, 0x2000
	s_nop 0
	global_load_lds_dwordx4 v[150:151], off
	s_waitcnt vmcnt(6)
	s_barrier
	s_setprio 1
	v_mfma_f32_16x16x32_bf16 v[28:31], v[202:205], v[166:169], v[28:31]
	v_mfma_f32_16x16x32_bf16 v[24:27], v[210:213], v[166:169], v[24:27]
	v_mfma_f32_16x16x32_bf16 v[20:23], v[202:205], v[174:177], v[20:23]
	v_mfma_f32_16x16x32_bf16 v[16:19], v[210:213], v[174:177], v[16:19]
	v_mfma_f32_16x16x32_bf16 v[12:15], v[202:205], v[182:185], v[12:15]
	v_mfma_f32_16x16x32_bf16 v[8:11], v[210:213], v[182:185], v[8:11]
	v_mfma_f32_16x16x32_bf16 v[4:7], v[202:205], v[194:197], v[4:7]
	v_mfma_f32_16x16x32_bf16 v[0:3], v[210:213], v[194:197], v[0:3]
	v_mfma_f32_16x16x32_bf16 v[28:31], v[206:209], v[170:173], v[28:31]
	v_mfma_f32_16x16x32_bf16 v[24:27], v[214:217], v[170:173], v[24:27]
	v_mfma_f32_16x16x32_bf16 v[20:23], v[206:209], v[178:181], v[20:23]
	v_mfma_f32_16x16x32_bf16 v[16:19], v[214:217], v[178:181], v[16:19]
	v_mfma_f32_16x16x32_bf16 v[12:15], v[206:209], v[186:189], v[12:15]
	v_mfma_f32_16x16x32_bf16 v[8:11], v[214:217], v[186:189], v[8:11]
	v_mfma_f32_16x16x32_bf16 v[4:7], v[206:209], v[198:201], v[4:7]
	v_mfma_f32_16x16x32_bf16 v[0:3], v[214:217], v[198:201], v[0:3]
	s_setprio 0
	s_add_i32 s81, s81, 2
	s_add_u32 s36, s36, 0x100
	s_addc_u32 s37, s37, 0
	s_cmp_gt_u32 s81, 29
	s_barrier
	s_cbranch_scc0 .LBB0_2088
	v_mov_b32_e32 v170, 0xbfb8aa3b
	v_mov_b32_e32 v172, 1.0
	v_mov_b64_e32 v[176:177], 0
	v_mov_b64_e32 v[178:179], 0
	v_pk_mul_f32 v[162:163], v[124:125], v[170:171] op_sel_hi:[1,0]
	s_add_u32 s36, s13, 0xffffff00
	v_pk_mul_f32 v[164:165], v[126:127], v[170:171] op_sel_hi:[1,0]
	s_addc_u32 s37, s51, -1
	v_pk_mul_f32 v[166:167], v[92:93], v[170:171] op_sel_hi:[1,0]
	s_ashr_i32 s13, s12, 31
	v_pk_mul_f32 v[168:169], v[94:95], v[170:171] op_sel_hi:[1,0]
	s_lshl_b64 s[38:39], s[12:13], 8
	v_exp_f32_e32 v162, v162
	v_lshl_add_u64 v[144:145], v[134:135], 0, s[38:39]
	v_exp_f32_e32 v163, v163
	v_mov_b64_e32 v[146:147], s[44:45]
	v_exp_f32_e32 v164, v164
	v_mad_u64_u32 v[146:147], s[54:55], v144, s64, v[146:147]
	v_exp_f32_e32 v165, v165
	s_lshl_b32 s13, s58, 7
	v_exp_f32_e32 v166, v166
	v_mov_b32_e32 v144, v147
	v_exp_f32_e32 v167, v167
	s_or_b32 s38, s13, s59
	v_exp_f32_e32 v168, v168
	v_mad_u64_u32 v[144:145], s[54:55], v145, s64, v[144:145]
	v_exp_f32_e32 v169, v169
	s_ashr_i32 s39, s38, 31
	v_mov_b32_e32 v147, v144
	v_lshl_add_u64 v[144:145], s[38:39], 1, v[146:147]
	v_lshl_add_u64 v[144:145], v[144:145], 0, v[132:133]
	v_pk_add_f32 v[162:163], v[162:163], v[172:173] op_sel_hi:[1,0]
	v_pk_add_f32 v[164:165], v[164:165], v[172:173] op_sel_hi:[1,0]
	v_pk_add_f32 v[166:167], v[166:167], v[172:173] op_sel_hi:[1,0]
	v_pk_add_f32 v[168:169], v[168:169], v[172:173] op_sel_hi:[1,0]
	v_rcp_f32_e32 v162, v162
	v_rcp_f32_e32 v163, v163
	v_rcp_f32_e32 v164, v164
	v_rcp_f32_e32 v165, v165
	v_rcp_f32_e32 v166, v166
	v_rcp_f32_e32 v167, v167
	v_rcp_f32_e32 v168, v168
	v_rcp_f32_e32 v169, v169
	v_pk_mul_f32 v[162:163], v[124:125], v[162:163]
	v_pk_mul_f32 v[164:165], v[126:127], v[164:165]
	v_pk_mul_f32 v[166:167], v[92:93], v[166:167]
	v_pk_mul_f32 v[168:169], v[94:95], v[168:169]
	v_pk_mul_f32 v[162:163], v[120:121], v[162:163]
	v_pk_mul_f32 v[164:165], v[122:123], v[164:165]
	v_pk_mul_f32 v[166:167], v[88:89], v[166:167]
	v_pk_mul_f32 v[168:169], v[90:91], v[168:169]
	v_cvt_pk_bf16_f32 v150, v162, v163
	v_cvt_pk_bf16_f32 v151, v164, v165
	v_cvt_pk_bf16_f32 v152, v166, v167
	v_cvt_pk_bf16_f32 v153, v168, v169
	global_store_dwordx4 v[144:145], v[150:153], off
	v_add_co_u32_e32 v146, vcc, s65, v144
	s_nop 0
	v_addc_co_u32_e32 v147, vcc, 0, v145, vcc
	v_pk_mul_f32 v[162:163], v[116:117], v[170:171] op_sel_hi:[1,0]
	v_pk_mul_f32 v[164:165], v[118:119], v[170:171] op_sel_hi:[1,0]
	v_pk_mul_f32 v[166:167], v[84:85], v[170:171] op_sel_hi:[1,0]
	v_pk_mul_f32 v[168:169], v[86:87], v[170:171] op_sel_hi:[1,0]
	v_exp_f32_e32 v162, v162
	v_exp_f32_e32 v163, v163
	v_exp_f32_e32 v164, v164
	v_exp_f32_e32 v165, v165
	v_exp_f32_e32 v166, v166
	v_exp_f32_e32 v167, v167
	v_exp_f32_e32 v168, v168
	v_exp_f32_e32 v169, v169
	v_pk_add_f32 v[162:163], v[162:163], v[172:173] op_sel_hi:[1,0]
	v_pk_add_f32 v[164:165], v[164:165], v[172:173] op_sel_hi:[1,0]
; __device__ __forceinline__ unsigned cvt_pk_bf16(float lo, float hi) { unsigned r; asm volatile("v_cvt_pk_bf16_f32 %0, %1, %2" : "=v"(r) : "v"(lo), "v"(hi)); return r; }
; template <class Epi>
; __device__ __forceinline__ void gemm_phase(LAS unsigned char* lds, const Gemm g, const Sched& S, const Epi& E) {
;     ...
; #pragma unroll
;         for (int a = 0; a < 2; ++a)
; #pragma unroll
;             for (int b = 0; b < 2; ++b)
; #pragma unroll
;                 for (int m = 0; m < 4; ++m)
; #pragma unroll
;                     for (int n = 0; n < 2; ++n) acc[a][b][m][n] = (f32x4){0.f, 0.f, 0.f, 0.f};
;     __device__ __forceinline__ void operator()(AccRef acc, const Unit& u, int wr, int wc, int fr, int fq) const {
;     ...
;         for (int ai = 0; ai < 2; ++ai)
; #pragma unroll
;             for (int m = 0; m < 4; ++m) { const size_t row = (size_t)u.pm * 256 + ai * 128 + wr * 64 + m * 16 + fr; float o[8];
; #pragma unroll
;                 for (int bj = 0; bj < 2; ++bj) { const f32x4 gg = acc[ai][bj][m][0], uu = acc[ai][bj][m][1];
; #pragma unroll
;                     for (int j = 0; j < 4; ++j) o[4 * bj + j] = gg[j] * __builtin_amdgcn_rcpf(1.0f + __expf(-gg[j])) * uu[j]; }
;                 u32x4 w; w.x = cvt_pk_bf16(o[0], o[1]); w.y = cvt_pk_bf16(o[2], o[3]); w.z = cvt_pk_bf16(o[4], o[5]); w.w = cvt_pk_bf16(o[6], o[7]);
;                 *(u32x4*)(act + row * FF_ + (u.pn * 4 + wc) * 32 + 8 * fq) = w; }
	v_pk_add_f32 v[166:167], v[166:167], v[172:173] op_sel_hi:[1,0]
	v_pk_add_f32 v[168:169], v[168:169], v[172:173] op_sel_hi:[1,0]
	v_rcp_f32_e32 v162, v162
	v_rcp_f32_e32 v163, v163
	v_rcp_f32_e32 v164, v164
	v_rcp_f32_e32 v165, v165
	v_rcp_f32_e32 v166, v166
	v_rcp_f32_e32 v167, v167
	v_rcp_f32_e32 v168, v168
	v_rcp_f32_e32 v169, v169
	v_pk_mul_f32 v[162:163], v[116:117], v[162:163]
	v_pk_mul_f32 v[164:165], v[118:119], v[164:165]
	v_pk_mul_f32 v[166:167], v[84:85], v[166:167]
	v_pk_mul_f32 v[168:169], v[86:87], v[168:169]
	v_pk_mul_f32 v[162:163], v[112:113], v[162:163]
	v_pk_mul_f32 v[164:165], v[114:115], v[164:165]
	v_pk_mul_f32 v[166:167], v[80:81], v[166:167]
	v_pk_mul_f32 v[168:169], v[82:83], v[168:169]
	v_cvt_pk_bf16_f32 v150, v162, v163
	v_cvt_pk_bf16_f32 v151, v164, v165
	v_cvt_pk_bf16_f32 v152, v166, v167
	v_cvt_pk_bf16_f32 v153, v168, v169
	global_store_dwordx4 v[146:147], v[150:153], off
	v_mfma_f32_32x32x16_bf16 v[80:95], v[176:179], v[176:179], 0
	v_mfma_f32_32x32x16_bf16 v[112:127], v[176:179], v[176:179], 0
	v_add_co_u32_e32 v146, vcc, s66, v144
	s_nop 0
	v_addc_co_u32_e32 v147, vcc, 0, v145, vcc
	v_pk_mul_f32 v[162:163], v[108:109], v[170:171] op_sel_hi:[1,0]
	v_pk_mul_f32 v[164:165], v[110:111], v[170:171] op_sel_hi:[1,0]
	v_pk_mul_f32 v[166:167], v[76:77], v[170:171] op_sel_hi:[1,0]
	v_pk_mul_f32 v[168:169], v[78:79], v[170:171] op_sel_hi:[1,0]
	v_exp_f32_e32 v162, v162
	v_exp_f32_e32 v163, v163
	v_exp_f32_e32 v164, v164
	v_exp_f32_e32 v165, v165
	v_exp_f32_e32 v166, v166
	v_exp_f32_e32 v167, v167
	v_exp_f32_e32 v168, v168
	v_exp_f32_e32 v169, v169
	v_pk_add_f32 v[162:163], v[162:163], v[172:173] op_sel_hi:[1,0]
	v_pk_add_f32 v[164:165], v[164:165], v[172:173] op_sel_hi:[1,0]
	v_pk_add_f32 v[166:167], v[166:167], v[172:173] op_sel_hi:[1,0]
	v_pk_add_f32 v[168:169], v[168:169], v[172:173] op_sel_hi:[1,0]
	v_rcp_f32_e32 v162, v162
	v_rcp_f32_e32 v163, v163
	v_rcp_f32_e32 v164, v164
	v_rcp_f32_e32 v165, v165
	v_rcp_f32_e32 v166, v166
	v_rcp_f32_e32 v167, v167
	v_rcp_f32_e32 v168, v168
	v_rcp_f32_e32 v169, v169
	v_pk_mul_f32 v[162:163], v[108:109], v[162:163]
	v_pk_mul_f32 v[164:165], v[110:111], v[164:165]
	v_pk_mul_f32 v[166:167], v[76:77], v[166:167]
	v_pk_mul_f32 v[168:169], v[78:79], v[168:169]
	v_pk_mul_f32 v[162:163], v[104:105], v[162:163]
	v_pk_mul_f32 v[164:165], v[106:107], v[164:165]
	v_pk_mul_f32 v[166:167], v[72:73], v[166:167]
	v_pk_mul_f32 v[168:169], v[74:75], v[168:169]
	v_cvt_pk_bf16_f32 v150, v162, v163
	v_cvt_pk_bf16_f32 v151, v164, v165
	v_cvt_pk_bf16_f32 v152, v166, v167
	v_cvt_pk_bf16_f32 v153, v168, v169
	global_store_dwordx4 v[146:147], v[150:153], off
	v_add_co_u32_e32 v146, vcc, s67, v144
	s_nop 0
	v_addc_co_u32_e32 v147, vcc, 0, v145, vcc
	v_pk_mul_f32 v[162:163], v[100:101], v[170:171] op_sel_hi:[1,0]
	v_pk_mul_f32 v[164:165], v[102:103], v[170:171] op_sel_hi:[1,0]
	v_pk_mul_f32 v[166:167], v[68:69], v[170:171] op_sel_hi:[1,0]
	v_pk_mul_f32 v[168:169], v[70:71], v[170:171] op_sel_hi:[1,0]
	v_exp_f32_e32 v162, v162
	v_exp_f32_e32 v163, v163
	v_exp_f32_e32 v164, v164
	v_exp_f32_e32 v165, v165
	v_exp_f32_e32 v166, v166
	v_exp_f32_e32 v167, v167
	v_exp_f32_e32 v168, v168
	v_exp_f32_e32 v169, v169
	v_pk_add_f32 v[162:163], v[162:163], v[172:173] op_sel_hi:[1,0]
	v_pk_add_f32 v[164:165], v[164:165], v[172:173] op_sel_hi:[1,0]
	v_pk_add_f32 v[166:167], v[166:167], v[172:173] op_sel_hi:[1,0]
	v_pk_add_f32 v[168:169], v[168:169], v[172:173] op_sel_hi:[1,0]
	v_rcp_f32_e32 v162, v162
	v_rcp_f32_e32 v163, v163
	v_rcp_f32_e32 v164, v164
	v_rcp_f32_e32 v165, v165
	v_rcp_f32_e32 v166, v166
	v_rcp_f32_e32 v167, v167
	v_rcp_f32_e32 v168, v168
	v_rcp_f32_e32 v169, v169
	v_pk_mul_f32 v[162:163], v[100:101], v[162:163]
	v_pk_mul_f32 v[164:165], v[102:103], v[164:165]
	v_pk_mul_f32 v[166:167], v[68:69], v[166:167]
	v_pk_mul_f32 v[168:169], v[70:71], v[168:169]
	v_pk_mul_f32 v[162:163], v[96:97], v[162:163]
	v_pk_mul_f32 v[164:165], v[98:99], v[164:165]
	v_pk_mul_f32 v[166:167], v[64:65], v[166:167]
	v_pk_mul_f32 v[168:169], v[66:67], v[168:169]
	v_cvt_pk_bf16_f32 v150, v162, v163
	v_cvt_pk_bf16_f32 v151, v164, v165
	v_cvt_pk_bf16_f32 v152, v166, v167
	v_cvt_pk_bf16_f32 v153, v168, v169
	global_store_dwordx4 v[146:147], v[150:153], off
	v_mfma_f32_32x32x16_bf16 v[64:79], v[176:179], v[176:179], 0
	v_mfma_f32_32x32x16_bf16 v[96:111], v[176:179], v[176:179], 0
	v_add_co_u32_e32 v146, vcc, s70, v144
	s_nop 0
	v_addc_co_u32_e32 v147, vcc, 0, v145, vcc
	v_pk_mul_f32 v[162:163], v[60:61], v[170:171] op_sel_hi:[1,0]
	v_pk_mul_f32 v[164:165], v[62:63], v[170:171] op_sel_hi:[1,0]
	v_pk_mul_f32 v[166:167], v[28:29], v[170:171] op_sel_hi:[1,0]
	v_pk_mul_f32 v[168:169], v[30:31], v[170:171] op_sel_hi:[1,0]
	v_exp_f32_e32 v162, v162
	v_exp_f32_e32 v163, v163
	v_exp_f32_e32 v164, v164
	v_exp_f32_e32 v165, v165
	v_exp_f32_e32 v166, v166
	v_exp_f32_e32 v167, v167
	v_exp_f32_e32 v168, v168
	v_exp_f32_e32 v169, v169
	v_pk_add_f32 v[162:163], v[162:163], v[172:173] op_sel_hi:[1,0]
	v_pk_add_f32 v[164:165], v[164:165], v[172:173] op_sel_hi:[1,0]
	v_pk_add_f32 v[166:167], v[166:167], v[172:173] op_sel_hi:[1,0]
	v_pk_add_f32 v[168:169], v[168:169], v[172:173] op_sel_hi:[1,0]
	v_rcp_f32_e32 v162, v162
	v_rcp_f32_e32 v163, v163
	v_rcp_f32_e32 v164, v164
	v_rcp_f32_e32 v165, v165
	v_rcp_f32_e32 v166, v166
	v_rcp_f32_e32 v167, v167
	v_rcp_f32_e32 v168, v168
	v_rcp_f32_e32 v169, v169
	v_pk_mul_f32 v[162:163], v[60:61], v[162:163]
	v_pk_mul_f32 v[164:165], v[62:63], v[164:165]
	v_pk_mul_f32 v[166:167], v[28:29], v[166:167]
	v_pk_mul_f32 v[168:169], v[30:31], v[168:169]
; __device__ __forceinline__ unsigned cvt_pk_bf16(float lo, float hi) { unsigned r; asm volatile("v_cvt_pk_bf16_f32 %0, %1, %2" : "=v"(r) : "v"(lo), "v"(hi)); return r; }
; template <class Epi>
; __device__ __forceinline__ void gemm_phase(LAS unsigned char* lds, const Gemm g, const Sched& S, const Epi& E) {
;     ...
;         if (!has_next) break;
; #pragma unroll
;         for (int a = 0; a < 2; ++a)
; #pragma unroll
;             for (int b = 0; b < 2; ++b)
; #pragma unroll
;                 for (int m = 0; m < 4; ++m)
; #pragma unroll
;                     for (int n = 0; n < 2; ++n) acc[a][b][m][n] = (f32x4){0.f, 0.f, 0.f, 0.f};
;         cur = nxt; cA = nA; cB = nB; ++ui;
;     __device__ __forceinline__ void operator()(AccRef acc, const Unit& u, int wr, int wc, int fr, int fq) const {
;     ...
;         for (int ai = 0; ai < 2; ++ai)
; #pragma unroll
;             for (int m = 0; m < 4; ++m) { const size_t row = (size_t)u.pm * 256 + ai * 128 + wr * 64 + m * 16 + fr; float o[8];
; #pragma unroll
;                 for (int bj = 0; bj < 2; ++bj) { const f32x4 gg = acc[ai][bj][m][0], uu = acc[ai][bj][m][1];
; #pragma unroll
;                     for (int j = 0; j < 4; ++j) o[4 * bj + j] = gg[j] * __builtin_amdgcn_rcpf(1.0f + __expf(-gg[j])) * uu[j]; }
;                 u32x4 w; w.x = cvt_pk_bf16(o[0], o[1]); w.y = cvt_pk_bf16(o[2], o[3]); w.z = cvt_pk_bf16(o[4], o[5]); w.w = cvt_pk_bf16(o[6], o[7]);
;                 *(u32x4*)(act + row * FF_ + (u.pn * 4 + wc) * 32 + 8 * fq) = w; }
	v_pk_mul_f32 v[162:163], v[56:57], v[162:163]
	v_pk_mul_f32 v[164:165], v[58:59], v[164:165]
	v_pk_mul_f32 v[166:167], v[24:25], v[166:167]
	v_pk_mul_f32 v[168:169], v[26:27], v[168:169]
	v_cvt_pk_bf16_f32 v150, v162, v163
	v_cvt_pk_bf16_f32 v151, v164, v165
	v_cvt_pk_bf16_f32 v152, v166, v167
	v_cvt_pk_bf16_f32 v153, v168, v169
	global_store_dwordx4 v[146:147], v[150:153], off
	v_add_co_u32_e32 v146, vcc, s71, v144
	s_nop 0
	v_addc_co_u32_e32 v147, vcc, 0, v145, vcc
	v_pk_mul_f32 v[162:163], v[52:53], v[170:171] op_sel_hi:[1,0]
	v_pk_mul_f32 v[164:165], v[54:55], v[170:171] op_sel_hi:[1,0]
	v_pk_mul_f32 v[166:167], v[20:21], v[170:171] op_sel_hi:[1,0]
	v_pk_mul_f32 v[168:169], v[22:23], v[170:171] op_sel_hi:[1,0]
	v_exp_f32_e32 v162, v162
	v_exp_f32_e32 v163, v163
	v_exp_f32_e32 v164, v164
	v_exp_f32_e32 v165, v165
	v_exp_f32_e32 v166, v166
	v_exp_f32_e32 v167, v167
	v_exp_f32_e32 v168, v168
	v_exp_f32_e32 v169, v169
	v_pk_add_f32 v[162:163], v[162:163], v[172:173] op_sel_hi:[1,0]
	v_pk_add_f32 v[164:165], v[164:165], v[172:173] op_sel_hi:[1,0]
	v_pk_add_f32 v[166:167], v[166:167], v[172:173] op_sel_hi:[1,0]
	v_pk_add_f32 v[168:169], v[168:169], v[172:173] op_sel_hi:[1,0]
	v_rcp_f32_e32 v162, v162
	v_rcp_f32_e32 v163, v163
	v_rcp_f32_e32 v164, v164
	v_rcp_f32_e32 v165, v165
	v_rcp_f32_e32 v166, v166
	v_rcp_f32_e32 v167, v167
	v_rcp_f32_e32 v168, v168
	v_rcp_f32_e32 v169, v169
	v_pk_mul_f32 v[162:163], v[52:53], v[162:163]
	v_pk_mul_f32 v[164:165], v[54:55], v[164:165]
	v_pk_mul_f32 v[166:167], v[20:21], v[166:167]
	v_pk_mul_f32 v[168:169], v[22:23], v[168:169]
	v_pk_mul_f32 v[162:163], v[48:49], v[162:163]
	v_pk_mul_f32 v[164:165], v[50:51], v[164:165]
	v_pk_mul_f32 v[166:167], v[16:17], v[166:167]
	v_pk_mul_f32 v[168:169], v[18:19], v[168:169]
	v_cvt_pk_bf16_f32 v150, v162, v163
	v_cvt_pk_bf16_f32 v151, v164, v165
	v_cvt_pk_bf16_f32 v152, v166, v167
	v_cvt_pk_bf16_f32 v153, v168, v169
	global_store_dwordx4 v[146:147], v[150:153], off
	v_mfma_f32_32x32x16_bf16 v[16:31], v[176:179], v[176:179], 0
	v_mfma_f32_32x32x16_bf16 v[48:63], v[176:179], v[176:179], 0
	v_add_co_u32_e32 v146, vcc, s78, v144
	s_nop 0
	v_addc_co_u32_e32 v147, vcc, 0, v145, vcc
	v_pk_mul_f32 v[162:163], v[44:45], v[170:171] op_sel_hi:[1,0]
	v_pk_mul_f32 v[164:165], v[46:47], v[170:171] op_sel_hi:[1,0]
	v_pk_mul_f32 v[166:167], v[12:13], v[170:171] op_sel_hi:[1,0]
	v_pk_mul_f32 v[168:169], v[14:15], v[170:171] op_sel_hi:[1,0]
	v_exp_f32_e32 v162, v162
	v_exp_f32_e32 v163, v163
	v_exp_f32_e32 v164, v164
	v_exp_f32_e32 v165, v165
	v_exp_f32_e32 v166, v166
	v_exp_f32_e32 v167, v167
	v_exp_f32_e32 v168, v168
	v_exp_f32_e32 v169, v169
	v_pk_add_f32 v[162:163], v[162:163], v[172:173] op_sel_hi:[1,0]
	v_pk_add_f32 v[164:165], v[164:165], v[172:173] op_sel_hi:[1,0]
	v_pk_add_f32 v[166:167], v[166:167], v[172:173] op_sel_hi:[1,0]
	v_pk_add_f32 v[168:169], v[168:169], v[172:173] op_sel_hi:[1,0]
	v_rcp_f32_e32 v162, v162
	v_rcp_f32_e32 v163, v163
	v_rcp_f32_e32 v164, v164
	v_rcp_f32_e32 v165, v165
	v_rcp_f32_e32 v166, v166
	v_rcp_f32_e32 v167, v167
	v_rcp_f32_e32 v168, v168
	v_rcp_f32_e32 v169, v169
	v_pk_mul_f32 v[162:163], v[44:45], v[162:163]
	v_pk_mul_f32 v[164:165], v[46:47], v[164:165]
	v_pk_mul_f32 v[166:167], v[12:13], v[166:167]
	v_pk_mul_f32 v[168:169], v[14:15], v[168:169]
	v_pk_mul_f32 v[162:163], v[40:41], v[162:163]
	v_pk_mul_f32 v[164:165], v[42:43], v[164:165]
	v_pk_mul_f32 v[166:167], v[8:9], v[166:167]
	v_pk_mul_f32 v[168:169], v[10:11], v[168:169]
	v_cvt_pk_bf16_f32 v150, v162, v163
	v_cvt_pk_bf16_f32 v151, v164, v165
	v_cvt_pk_bf16_f32 v152, v166, v167
	v_cvt_pk_bf16_f32 v153, v168, v169
	global_store_dwordx4 v[146:147], v[150:153], off
	v_add_co_u32_e32 v144, vcc, 0x1e4000, v144
	v_addc_co_u32_e32 v145, vcc, 0, v145, vcc
	s_andn2_b64 vcc, exec, s[10:11]
	v_pk_mul_f32 v[162:163], v[36:37], v[170:171] op_sel_hi:[1,0]
	v_pk_mul_f32 v[164:165], v[38:39], v[170:171] op_sel_hi:[1,0]
	v_pk_mul_f32 v[166:167], v[4:5], v[170:171] op_sel_hi:[1,0]
	v_pk_mul_f32 v[168:169], v[6:7], v[170:171] op_sel_hi:[1,0]
	v_exp_f32_e32 v162, v162
	v_exp_f32_e32 v163, v163
	v_exp_f32_e32 v164, v164
	v_exp_f32_e32 v165, v165
	v_exp_f32_e32 v166, v166
	v_exp_f32_e32 v167, v167
	v_exp_f32_e32 v168, v168
	v_exp_f32_e32 v169, v169
	v_pk_add_f32 v[162:163], v[162:163], v[172:173] op_sel_hi:[1,0]
	v_pk_add_f32 v[164:165], v[164:165], v[172:173] op_sel_hi:[1,0]
	v_pk_add_f32 v[166:167], v[166:167], v[172:173] op_sel_hi:[1,0]
	v_pk_add_f32 v[168:169], v[168:169], v[172:173] op_sel_hi:[1,0]
	v_rcp_f32_e32 v162, v162
	v_rcp_f32_e32 v163, v163
	v_rcp_f32_e32 v164, v164
	v_rcp_f32_e32 v165, v165
	v_rcp_f32_e32 v166, v166
	v_rcp_f32_e32 v167, v167
	v_rcp_f32_e32 v168, v168
	v_rcp_f32_e32 v169, v169
	v_pk_mul_f32 v[162:163], v[36:37], v[162:163]
	v_pk_mul_f32 v[164:165], v[38:39], v[164:165]
	v_pk_mul_f32 v[166:167], v[4:5], v[166:167]
	v_pk_mul_f32 v[168:169], v[6:7], v[168:169]
	v_pk_mul_f32 v[162:163], v[32:33], v[162:163]
	v_pk_mul_f32 v[164:165], v[34:35], v[164:165]
	v_pk_mul_f32 v[166:167], v[0:1], v[166:167]
	v_pk_mul_f32 v[168:169], v[2:3], v[168:169]
	v_cvt_pk_bf16_f32 v150, v162, v163
	v_cvt_pk_bf16_f32 v151, v164, v165
	v_cvt_pk_bf16_f32 v152, v166, v167
	v_cvt_pk_bf16_f32 v153, v168, v169
	global_store_dwordx4 v[144:145], v[150:153], off
	v_mfma_f32_32x32x16_bf16 v[0:15], v[176:179], v[176:179], 0
	v_mfma_f32_32x32x16_bf16 v[32:47], v[176:179], v[176:179], 0
	s_cbranch_vccz .LBB0_2084
	s_mov_b64 s[22:23], s[36:37]
	s_andn2_b64 vcc, exec, s[8:9]
	s_mov_b64 s[36:37], s[22:23]
	s_cbranch_vccnz .LBB0_2085

; #define PG8_STAGE(bufoff, gbase, voff) do { _Pragma("unroll") for (int _i = 0; _i < 2; ++_i) \
;         __builtin_amdgcn_global_load_lds((const unsigned*)((const char*)(gbase) + (voff)[_i]), (LAS unsigned*)(lds + (bufoff) + ldsw + _i * 8192), 16, 0, 0); } while (0)
; #define PG8_LDA(dst, b, h) do { _Pragma("unroll") for (int m = 0; m < 4; ++m) _Pragma("unroll") for (int k = 0; k < 2; ++k) dst[m][k] = *(const LAS bf16x8*)(lds + PG8_SA(b, h) + aoff + m * 2048 + k * 1024); } while (0)
; #define PG8_LDB(dst, b, h) do { _Pragma("unroll") for (int n = 0; n < 2; ++n) _Pragma("unroll") for (int k = 0; k < 2; ++k) dst[n][k] = *(const LAS bf16x8*)(lds + PG8_SB(b, h) + boff + n * 2048 + k * 1024); } while (0)
; #define PG8_MMA(ai, bj, At, Bt) do { __builtin_amdgcn_s_setprio(1); _Pragma("unroll") for (int m = 0; m < 4; ++m) _Pragma("unroll") for (int n = 0; n < 2; ++n) _Pragma("unroll") for (int k = 0; k < 2; ++k) \
;         acc[ai][bj][m][n] = __builtin_amdgcn_mfma_f32_16x16x32_bf16(Bt[n][k], At[m][k], acc[ai][bj][m][n], 0, 0, 0); __builtin_amdgcn_s_setprio(0); } while (0)
; #define PG8_WAIT_L(n) asm volatile("s_waitcnt lgkmcnt(" #n ")" ::: "memory")
; #define PG8_BAR __builtin_amdgcn_s_barrier()
; #define PG8_SCHED __builtin_amdgcn_sched_barrier(0)
; template <class Epi>
; __device__ __forceinline__ void gemm_phase(LAS unsigned char* lds, const Gemm g, const Sched& S, const Epi& E) {
;     ...
;             PG8_LDB(B0, 0, 0); PG8_SCHED; PG8_LDA(At, 0, 0); PG8_STAGE(PG8_SA(1, 1), a1 + hstepA, voffA);
;             PG8_WAIT_L(8); PG8_BAR; PG8_WAIT_L(0); PG8_MMA(0, 0, At, B0); PG8_BAR; PG8_SCHED;
;             PG8_LDB(B1, 0, 1); PG8_STAGE(PG8_SB(0, 0), b2, voffB);
;             PG8_BAR; PG8_WAIT_L(0); PG8_MMA(0, 1, At, B1); PG8_BAR;
;             PG8_LDA(At, 0, 1); PG8_STAGE(PG8_SA(0, 0), a2, voffA);
;             PG8_BAR; PG8_WAIT_L(0); PG8_MMA(1, 0, At, B0); PG8_BAR; PG8_SCHED;
.LBB0_3085:
	v_add_u32_e32 v162, s54, v148
	s_add_u32 s36, s12, s24
	ds_read_b128 v[150:153], v162
	ds_read_b128 v[154:157], v162 offset:1024
	ds_read_b128 v[158:161], v162 offset:2048
	ds_read_b128 v[162:165], v162 offset:3072
	s_addc_u32 s37, s13, s25
	s_add_u32 s36, s36, 0x100
	s_addc_u32 s37, s37, 0
	s_add_u32 s70, s11, s24
	s_addc_u32 s71, s64, s25
	s_cmpk_eq_i32 s24, 0xf00
	s_cselect_b32 s39, s19, s37
	s_cselect_b32 s38, s65, s36
	s_cselect_b32 s37, s17, s71
	s_cselect_b32 s36, s66, s70
	v_lshl_add_u64 v[190:191], v[144:145], 0, s[24:25]
	s_add_i32 m0, s40, 0xc000
	ds_read_b128 v[166:169], v149
	ds_read_b128 v[170:173], v149 offset:1024
	ds_read_b128 v[174:177], v149 offset:2048
	ds_read_b128 v[178:181], v149 offset:3072
	ds_read_b128 v[182:185], v149 offset:4096
	ds_read_b128 v[186:189], v149 offset:5120
	ds_read_b128 v[194:197], v149 offset:6144
	ds_read_b128 v[198:201], v149 offset:7168
	global_load_lds_dwordx4 v[190:191], off
	v_lshl_add_u64 v[190:191], v[146:147], 0, s[24:25]
	s_add_i32 m0, s40, 0xe000
	s_nop 0
	global_load_lds_dwordx4 v[190:191], off
	s_waitcnt lgkmcnt(8)
	s_barrier
	s_waitcnt lgkmcnt(0)
	s_setprio 1
	s_waitcnt lgkmcnt(0)
	v_mfma_f32_16x16x32_bf16 v[124:127], v[150:153], v[166:169], v[124:127]
	v_mfma_f32_16x16x32_bf16 v[120:123], v[158:161], v[166:169], v[120:123]
	v_mfma_f32_16x16x32_bf16 v[116:119], v[150:153], v[174:177], v[116:119]
	v_mfma_f32_16x16x32_bf16 v[112:115], v[158:161], v[174:177], v[112:115]
	v_mfma_f32_16x16x32_bf16 v[108:111], v[150:153], v[182:185], v[108:111]
	v_mfma_f32_16x16x32_bf16 v[104:107], v[158:161], v[182:185], v[104:107]
	v_mfma_f32_16x16x32_bf16 v[100:103], v[150:153], v[194:197], v[100:103]
	v_mfma_f32_16x16x32_bf16 v[96:99], v[158:161], v[194:197], v[96:99]
	v_mfma_f32_16x16x32_bf16 v[124:127], v[154:157], v[170:173], v[124:127]
	v_mfma_f32_16x16x32_bf16 v[120:123], v[162:165], v[170:173], v[120:123]
	v_mfma_f32_16x16x32_bf16 v[116:119], v[154:157], v[178:181], v[116:119]
	v_mfma_f32_16x16x32_bf16 v[112:115], v[162:165], v[178:181], v[112:115]
	v_mfma_f32_16x16x32_bf16 v[108:111], v[154:157], v[186:189], v[108:111]
	v_mfma_f32_16x16x32_bf16 v[104:107], v[162:165], v[186:189], v[104:107]
	v_mfma_f32_16x16x32_bf16 v[100:103], v[154:157], v[198:201], v[100:103]
	v_mfma_f32_16x16x32_bf16 v[96:99], v[162:165], v[198:201], v[96:99]
	s_setprio 0
	s_barrier
	v_add_u32_e32 v190, s55, v148
	s_add_i32 s70, s54, s34
	ds_read_b128 v[202:205], v190
	ds_read_b128 v[206:209], v190 offset:1024
	ds_read_b128 v[210:213], v190 offset:2048
	ds_read_b128 v[214:217], v190 offset:3072
	v_lshl_add_u64 v[190:191], s[36:37], 0, v[130:131]
	s_mov_b32 m0, s70
	v_lshl_add_u64 v[218:219], s[36:37], 0, v[128:129]
	global_load_lds_dwordx4 v[190:191], off
	s_add_i32 m0, s70, 0x2000
	s_nop 0
	global_load_lds_dwordx4 v[218:219], off
	s_barrier
	s_waitcnt lgkmcnt(0)
	s_setprio 1
	s_waitcnt lgkmcnt(0)
	v_mfma_f32_16x16x32_bf16 v[92:95], v[202:205], v[166:169], v[92:95]
	v_mfma_f32_16x16x32_bf16 v[88:91], v[210:213], v[166:169], v[88:91]
	v_mfma_f32_16x16x32_bf16 v[84:87], v[202:205], v[174:177], v[84:87]
	v_mfma_f32_16x16x32_bf16 v[80:83], v[210:213], v[174:177], v[80:83]
	v_mfma_f32_16x16x32_bf16 v[76:79], v[202:205], v[182:185], v[76:79]
	v_mfma_f32_16x16x32_bf16 v[72:75], v[210:213], v[182:185], v[72:75]
	v_mfma_f32_16x16x32_bf16 v[68:71], v[202:205], v[194:197], v[68:71]
	v_mfma_f32_16x16x32_bf16 v[64:67], v[210:213], v[194:197], v[64:67]
	v_mfma_f32_16x16x32_bf16 v[92:95], v[206:209], v[170:173], v[92:95]
	v_mfma_f32_16x16x32_bf16 v[88:91], v[214:217], v[170:173], v[88:91]
	v_mfma_f32_16x16x32_bf16 v[84:87], v[206:209], v[178:181], v[84:87]
	v_mfma_f32_16x16x32_bf16 v[80:83], v[214:217], v[178:181], v[80:83]
	v_mfma_f32_16x16x32_bf16 v[76:79], v[206:209], v[186:189], v[76:79]
	v_mfma_f32_16x16x32_bf16 v[72:75], v[214:217], v[186:189], v[72:75]
	v_mfma_f32_16x16x32_bf16 v[68:71], v[206:209], v[198:201], v[68:71]
	v_mfma_f32_16x16x32_bf16 v[64:67], v[214:217], v[198:201], v[64:67]
	s_setprio 0
	s_mov_b32 m0, s40
	v_lshl_add_u64 v[220:221], s[38:39], 0, v[130:131]
	s_barrier
	ds_read_b128 v[166:169], v149 offset:16384
	ds_read_b128 v[170:173], v149 offset:17408
	ds_read_b128 v[174:177], v149 offset:18432
	ds_read_b128 v[178:181], v149 offset:19456
	ds_read_b128 v[182:185], v149 offset:20480
	ds_read_b128 v[186:189], v149 offset:21504
	ds_read_b128 v[194:197], v149 offset:22528
	ds_read_b128 v[198:201], v149 offset:23552
	global_load_lds_dwordx4 v[220:221], off
	v_lshl_add_u64 v[222:223], s[38:39], 0, v[128:129]
	s_mov_b32 m0, s41
	s_nop 0
	global_load_lds_dwordx4 v[222:223], off
	s_barrier
	s_waitcnt lgkmcnt(0)
	s_setprio 1
	s_waitcnt lgkmcnt(0)
	v_mfma_f32_16x16x32_bf16 v[60:63], v[150:153], v[166:169], v[60:63]
	v_mfma_f32_16x16x32_bf16 v[56:59], v[158:161], v[166:169], v[56:59]
	v_mfma_f32_16x16x32_bf16 v[52:55], v[150:153], v[174:177], v[52:55]
	v_mfma_f32_16x16x32_bf16 v[48:51], v[158:161], v[174:177], v[48:51]
	v_mfma_f32_16x16x32_bf16 v[44:47], v[150:153], v[182:185], v[44:47]
	v_mfma_f32_16x16x32_bf16 v[40:43], v[158:161], v[182:185], v[40:43]
	v_mfma_f32_16x16x32_bf16 v[36:39], v[150:153], v[194:197], v[36:39]
	v_mfma_f32_16x16x32_bf16 v[32:35], v[158:161], v[194:197], v[32:35]
	v_mfma_f32_16x16x32_bf16 v[60:63], v[154:157], v[170:173], v[60:63]
	v_mfma_f32_16x16x32_bf16 v[56:59], v[162:165], v[170:173], v[56:59]
	v_mfma_f32_16x16x32_bf16 v[52:55], v[154:157], v[178:181], v[52:55]
	v_mfma_f32_16x16x32_bf16 v[48:51], v[162:165], v[178:181], v[48:51]
	v_mfma_f32_16x16x32_bf16 v[44:47], v[154:157], v[186:189], v[44:47]
	v_mfma_f32_16x16x32_bf16 v[40:43], v[162:165], v[186:189], v[40:43]
	v_mfma_f32_16x16x32_bf16 v[36:39], v[154:157], v[198:201], v[36:39]
	v_mfma_f32_16x16x32_bf16 v[32:35], v[162:165], v[198:201], v[32:35]
	s_setprio 0
	s_barrier
; #define PG8_STAGE(bufoff, gbase, voff) do { _Pragma("unroll") for (int _i = 0; _i < 2; ++_i) \
;         __builtin_amdgcn_global_load_lds((const unsigned*)((const char*)(gbase) + (voff)[_i]), (LAS unsigned*)(lds + (bufoff) + ldsw + _i * 8192), 16, 0, 0); } while (0)
; #define PG8_LDA(dst, b, h) do { _Pragma("unroll") for (int m = 0; m < 4; ++m) _Pragma("unroll") for (int k = 0; k < 2; ++k) dst[m][k] = *(const LAS bf16x8*)(lds + PG8_SA(b, h) + aoff + m * 2048 + k * 1024); } while (0)
; #define PG8_LDB(dst, b, h) do { _Pragma("unroll") for (int n = 0; n < 2; ++n) _Pragma("unroll") for (int k = 0; k < 2; ++k) dst[n][k] = *(const LAS bf16x8*)(lds + PG8_SB(b, h) + boff + n * 2048 + k * 1024); } while (0)
; #define PG8_MMA(ai, bj, At, Bt) do { __builtin_amdgcn_s_setprio(1); _Pragma("unroll") for (int m = 0; m < 4; ++m) _Pragma("unroll") for (int n = 0; n < 2; ++n) _Pragma("unroll") for (int k = 0; k < 2; ++k) \
;         acc[ai][bj][m][n] = __builtin_amdgcn_mfma_f32_16x16x32_bf16(Bt[n][k], At[m][k], acc[ai][bj][m][n], 0, 0, 0); __builtin_amdgcn_s_setprio(0); } while (0)
; #define PG8_WAIT_V(n) asm volatile("s_waitcnt vmcnt(" #n ")" ::: "memory")
; #define PG8_WAIT_L(n) asm volatile("s_waitcnt lgkmcnt(" #n ")" ::: "memory")
; #define PG8_BAR __builtin_amdgcn_s_barrier()
; #define PG8_SCHED __builtin_amdgcn_sched_barrier(0)
; template <class Epi>
; __device__ __forceinline__ void gemm_phase(LAS unsigned char* lds, const Gemm g, const Sched& S, const Epi& E) {
;     ...
;             PG8_STAGE(PG8_SB(0, 1), b2 + hstepB, voffB);
;             PG8_WAIT_V(6); PG8_BAR; PG8_MMA(1, 1, At, B1); PG8_BAR;
;             PG8_LDB(B0, 1, 0); PG8_SCHED; PG8_LDA(At, 1, 0); PG8_STAGE(PG8_SA(0, 1), a2 + hstepA, voffA);
;             PG8_WAIT_L(8); PG8_BAR; PG8_WAIT_L(0); PG8_MMA(0, 0, At, B0); PG8_BAR; PG8_SCHED;
;             PG8_LDB(B1, 1, 1); PG8_STAGE(PG8_SB(1, 0), b3, voffB);
;             PG8_BAR; PG8_WAIT_L(0); PG8_MMA(0, 1, At, B1); PG8_BAR;
;             PG8_LDA(At, 1, 1); PG8_STAGE(PG8_SA(1, 0), a3, voffA);
	s_add_u32 s70, s36, 0x80000
	s_addc_u32 s71, s37, 0
	s_add_i32 s72, s55, s34
	v_lshl_add_u64 v[150:151], s[70:71], 0, v[130:131]
	s_mov_b32 m0, s72
	s_nop 0
	global_load_lds_dwordx4 v[150:151], off
	v_lshl_add_u64 v[150:151], s[70:71], 0, v[128:129]
	s_add_i32 m0, s72, 0x2000
	s_nop 0
	global_load_lds_dwordx4 v[150:151], off
	s_waitcnt vmcnt(6)
	s_barrier
	s_setprio 1
	v_mfma_f32_16x16x32_bf16 v[28:31], v[202:205], v[166:169], v[28:31]
	v_mfma_f32_16x16x32_bf16 v[24:27], v[210:213], v[166:169], v[24:27]
	v_mfma_f32_16x16x32_bf16 v[20:23], v[202:205], v[174:177], v[20:23]
	v_mfma_f32_16x16x32_bf16 v[16:19], v[210:213], v[174:177], v[16:19]
	v_mfma_f32_16x16x32_bf16 v[12:15], v[202:205], v[182:185], v[12:15]
	v_mfma_f32_16x16x32_bf16 v[8:11], v[210:213], v[182:185], v[8:11]
	v_mfma_f32_16x16x32_bf16 v[4:7], v[202:205], v[194:197], v[4:7]
	v_mfma_f32_16x16x32_bf16 v[0:3], v[210:213], v[194:197], v[0:3]
	v_mfma_f32_16x16x32_bf16 v[28:31], v[206:209], v[170:173], v[28:31]
	v_mfma_f32_16x16x32_bf16 v[24:27], v[214:217], v[170:173], v[24:27]
	v_mfma_f32_16x16x32_bf16 v[20:23], v[206:209], v[178:181], v[20:23]
	v_mfma_f32_16x16x32_bf16 v[16:19], v[214:217], v[178:181], v[16:19]
	v_mfma_f32_16x16x32_bf16 v[12:15], v[206:209], v[186:189], v[12:15]
	v_mfma_f32_16x16x32_bf16 v[8:11], v[214:217], v[186:189], v[8:11]
	v_mfma_f32_16x16x32_bf16 v[4:7], v[206:209], v[198:201], v[4:7]
	v_mfma_f32_16x16x32_bf16 v[0:3], v[214:217], v[198:201], v[0:3]
	s_setprio 0
	s_add_i32 s70, 0, 0x18000
	v_add_u32_e32 v162, s70, v148
	s_barrier
	ds_read_b128 v[150:153], v162
	ds_read_b128 v[154:157], v162 offset:1024
	ds_read_b128 v[158:161], v162 offset:2048
	ds_read_b128 v[162:165], v162 offset:3072
	s_add_u32 s38, s38, 0x80000
	s_addc_u32 s39, s39, 0
	s_mov_b32 m0, s43
	v_lshl_add_u64 v[202:203], s[38:39], 0, v[130:131]
	ds_read_b128 v[166:169], v149 offset:32768
	ds_read_b128 v[170:173], v149 offset:33792
	ds_read_b128 v[174:177], v149 offset:34816
	ds_read_b128 v[178:181], v149 offset:35840
	ds_read_b128 v[182:185], v149 offset:36864
	ds_read_b128 v[186:189], v149 offset:37888
	ds_read_b128 v[194:197], v149 offset:38912
	ds_read_b128 v[198:201], v149 offset:39936
	global_load_lds_dwordx4 v[202:203], off
	v_lshl_add_u64 v[202:203], s[38:39], 0, v[128:129]
	s_mov_b32 m0, s46
	s_nop 0
	global_load_lds_dwordx4 v[202:203], off
	s_waitcnt lgkmcnt(8)
	s_barrier
	s_waitcnt lgkmcnt(0)
	s_setprio 1
	s_waitcnt lgkmcnt(0)
	v_mfma_f32_16x16x32_bf16 v[124:127], v[150:153], v[166:169], v[124:127]
	v_mfma_f32_16x16x32_bf16 v[120:123], v[158:161], v[166:169], v[120:123]
	v_mfma_f32_16x16x32_bf16 v[116:119], v[150:153], v[174:177], v[116:119]
	v_mfma_f32_16x16x32_bf16 v[112:115], v[158:161], v[174:177], v[112:115]
	v_mfma_f32_16x16x32_bf16 v[108:111], v[150:153], v[182:185], v[108:111]
	v_mfma_f32_16x16x32_bf16 v[104:107], v[158:161], v[182:185], v[104:107]
	v_mfma_f32_16x16x32_bf16 v[100:103], v[150:153], v[194:197], v[100:103]
	v_mfma_f32_16x16x32_bf16 v[96:99], v[158:161], v[194:197], v[96:99]
	v_mfma_f32_16x16x32_bf16 v[124:127], v[154:157], v[170:173], v[124:127]
	v_mfma_f32_16x16x32_bf16 v[120:123], v[162:165], v[170:173], v[120:123]
	v_mfma_f32_16x16x32_bf16 v[116:119], v[154:157], v[178:181], v[116:119]
	v_mfma_f32_16x16x32_bf16 v[112:115], v[162:165], v[178:181], v[112:115]
	v_mfma_f32_16x16x32_bf16 v[108:111], v[154:157], v[186:189], v[108:111]
	v_mfma_f32_16x16x32_bf16 v[104:107], v[162:165], v[186:189], v[104:107]
	v_mfma_f32_16x16x32_bf16 v[100:103], v[154:157], v[198:201], v[100:103]
	v_mfma_f32_16x16x32_bf16 v[96:99], v[162:165], v[198:201], v[96:99]
	s_setprio 0
	s_barrier
	s_add_i32 s38, 0, 0x1c000
	s_add_i32 s39, s70, s34
	v_add_u32_e32 v214, s38, v148
	v_lshl_add_u64 v[190:191], v[190:191], 0, s[14:15]
	s_mov_b32 m0, s39
	ds_read_b128 v[202:205], v214
	ds_read_b128 v[206:209], v214 offset:1024
	ds_read_b128 v[210:213], v214 offset:2048
	ds_read_b128 v[214:217], v214 offset:3072
	global_load_lds_dwordx4 v[190:191], off
	v_lshl_add_u64 v[190:191], v[218:219], 0, s[14:15]
	s_add_i32 m0, s39, 0x2000
	s_nop 0
	global_load_lds_dwordx4 v[190:191], off
	s_barrier
	s_waitcnt lgkmcnt(0)
	s_setprio 1
	s_waitcnt lgkmcnt(0)
	v_mfma_f32_16x16x32_bf16 v[92:95], v[202:205], v[166:169], v[92:95]
	v_mfma_f32_16x16x32_bf16 v[88:91], v[210:213], v[166:169], v[88:91]
	v_mfma_f32_16x16x32_bf16 v[84:87], v[202:205], v[174:177], v[84:87]
	v_mfma_f32_16x16x32_bf16 v[80:83], v[210:213], v[174:177], v[80:83]
	v_mfma_f32_16x16x32_bf16 v[76:79], v[202:205], v[182:185], v[76:79]
	v_mfma_f32_16x16x32_bf16 v[72:75], v[210:213], v[182:185], v[72:75]
	v_mfma_f32_16x16x32_bf16 v[68:71], v[202:205], v[194:197], v[68:71]
	v_mfma_f32_16x16x32_bf16 v[64:67], v[210:213], v[194:197], v[64:67]
	v_mfma_f32_16x16x32_bf16 v[92:95], v[206:209], v[170:173], v[92:95]
	v_mfma_f32_16x16x32_bf16 v[88:91], v[214:217], v[170:173], v[88:91]
	v_mfma_f32_16x16x32_bf16 v[84:87], v[206:209], v[178:181], v[84:87]
	v_mfma_f32_16x16x32_bf16 v[80:83], v[214:217], v[178:181], v[80:83]
	v_mfma_f32_16x16x32_bf16 v[76:79], v[206:209], v[186:189], v[76:79]
	v_mfma_f32_16x16x32_bf16 v[72:75], v[214:217], v[186:189], v[72:75]
	v_mfma_f32_16x16x32_bf16 v[68:71], v[206:209], v[198:201], v[68:71]
	v_mfma_f32_16x16x32_bf16 v[64:67], v[214:217], v[198:201], v[64:67]
	s_setprio 0
	s_mov_b32 m0, s52
	v_lshl_add_u64 v[190:191], v[220:221], 0, s[14:15]
	s_barrier
	ds_read_b128 v[166:169], v149 offset:49152
	ds_read_b128 v[170:173], v149 offset:50176
	ds_read_b128 v[174:177], v149 offset:51200
	ds_read_b128 v[178:181], v149 offset:52224
	ds_read_b128 v[182:185], v149 offset:53248
	ds_read_b128 v[186:189], v149 offset:54272
	ds_read_b128 v[194:197], v149 offset:55296
	ds_read_b128 v[198:201], v149 offset:56320
	global_load_lds_dwordx4 v[190:191], off
	v_lshl_add_u64 v[190:191], v[222:223], 0, s[14:15]
	s_mov_b32 m0, s53
	s_nop 0
	global_load_lds_dwordx4 v[190:191], off
	s_barrier
; __device__ __forceinline__ unsigned cvt_pk_bf16(float lo, float hi) { unsigned r; asm volatile("v_cvt_pk_bf16_f32 %0, %1, %2" : "=v"(r) : "v"(lo), "v"(hi)); return r; }
; #define PG8_STAGE(bufoff, gbase, voff) do { _Pragma("unroll") for (int _i = 0; _i < 2; ++_i) \
;         __builtin_amdgcn_global_load_lds((const unsigned*)((const char*)(gbase) + (voff)[_i]), (LAS unsigned*)(lds + (bufoff) + ldsw + _i * 8192), 16, 0, 0); } while (0)
; #define PG8_MMA(ai, bj, At, Bt) do { __builtin_amdgcn_s_setprio(1); _Pragma("unroll") for (int m = 0; m < 4; ++m) _Pragma("unroll") for (int n = 0; n < 2; ++n) _Pragma("unroll") for (int k = 0; k < 2; ++k) \
;         acc[ai][bj][m][n] = __builtin_amdgcn_mfma_f32_16x16x32_bf16(Bt[n][k], At[m][k], acc[ai][bj][m][n], 0, 0, 0); __builtin_amdgcn_s_setprio(0); } while (0)
; #define PG8_WAIT_V(n) asm volatile("s_waitcnt vmcnt(" #n ")" ::: "memory")
; #define PG8_WAIT_L(n) asm volatile("s_waitcnt lgkmcnt(" #n ")" ::: "memory")
; #define PG8_BAR __builtin_amdgcn_s_barrier()
; #define PG8_SCHED __builtin_amdgcn_sched_barrier(0)
; template <class Epi>
; __device__ __forceinline__ void gemm_phase(LAS unsigned char* lds, const Gemm g, const Sched& S, const Epi& E) {
;     ...
;             PG8_BAR; PG8_WAIT_L(0); PG8_MMA(1, 0, At, B0); PG8_BAR; PG8_SCHED;
;             PG8_STAGE(PG8_SB(1, 1), b3 + hstepB, voffB);
;             PG8_WAIT_V(6); PG8_BAR; PG8_MMA(1, 1, At, B1); PG8_BAR;
;     __device__ __forceinline__ void operator()(AccRef acc, const Unit& u, int wr, int wc, int fr, int fq) const {
;     ...
;         for (int ai = 0; ai < 2; ++ai)
; #pragma unroll
;             for (int m = 0; m < 4; ++m) { const size_t row = (size_t)u.pm * 256 + ai * 128 + wr * 64 + m * 16 + fr; float o[8];
; #pragma unroll
;                 for (int bj = 0; bj < 2; ++bj) { const f32x4 gg = acc[ai][bj][m][0], uu = acc[ai][bj][m][1];
; #pragma unroll
;                     for (int j = 0; j < 4; ++j) o[4 * bj + j] = gg[j] * __builtin_amdgcn_rcpf(1.0f + __expf(-gg[j])) * uu[j]; }
;                 u32x4 w; w.x = cvt_pk_bf16(o[0], o[1]); w.y = cvt_pk_bf16(o[2], o[3]); w.z = cvt_pk_bf16(o[4], o[5]); w.w = cvt_pk_bf16(o[6], o[7]);
;                 *(u32x4*)(act + row * FF_ + (u.pn * 4 + wc) * 32 + 8 * fq) = w; }
	s_waitcnt lgkmcnt(0)
	s_setprio 1
	s_waitcnt lgkmcnt(0)
	v_mfma_f32_16x16x32_bf16 v[60:63], v[150:153], v[166:169], v[60:63]
	v_mfma_f32_16x16x32_bf16 v[56:59], v[158:161], v[166:169], v[56:59]
	v_mfma_f32_16x16x32_bf16 v[52:55], v[150:153], v[174:177], v[52:55]
	v_mfma_f32_16x16x32_bf16 v[48:51], v[158:161], v[174:177], v[48:51]
	v_mfma_f32_16x16x32_bf16 v[44:47], v[150:153], v[182:185], v[44:47]
	v_mfma_f32_16x16x32_bf16 v[40:43], v[158:161], v[182:185], v[40:43]
	v_mfma_f32_16x16x32_bf16 v[36:39], v[150:153], v[194:197], v[36:39]
	v_mfma_f32_16x16x32_bf16 v[32:35], v[158:161], v[194:197], v[32:35]
	v_mfma_f32_16x16x32_bf16 v[60:63], v[154:157], v[170:173], v[60:63]
	v_mfma_f32_16x16x32_bf16 v[56:59], v[162:165], v[170:173], v[56:59]
	v_mfma_f32_16x16x32_bf16 v[52:55], v[154:157], v[178:181], v[52:55]
	v_mfma_f32_16x16x32_bf16 v[48:51], v[162:165], v[178:181], v[48:51]
	v_mfma_f32_16x16x32_bf16 v[44:47], v[154:157], v[186:189], v[44:47]
	v_mfma_f32_16x16x32_bf16 v[40:43], v[162:165], v[186:189], v[40:43]
	v_mfma_f32_16x16x32_bf16 v[36:39], v[154:157], v[198:201], v[36:39]
	v_mfma_f32_16x16x32_bf16 v[32:35], v[162:165], v[198:201], v[32:35]
	s_setprio 0
	s_barrier
	s_add_u32 s36, s36, 0x80080
	s_addc_u32 s37, s37, 0
	s_add_i32 s38, s38, s34
	v_lshl_add_u64 v[150:151], s[36:37], 0, v[130:131]
	s_mov_b32 m0, s38
	s_nop 0
	global_load_lds_dwordx4 v[150:151], off
	v_lshl_add_u64 v[150:151], s[36:37], 0, v[128:129]
	s_add_i32 m0, s38, 0x2000
	s_nop 0
	global_load_lds_dwordx4 v[150:151], off
	s_waitcnt vmcnt(6)
	s_barrier
	s_setprio 1
	v_mfma_f32_16x16x32_bf16 v[28:31], v[202:205], v[166:169], v[28:31]
	v_mfma_f32_16x16x32_bf16 v[24:27], v[210:213], v[166:169], v[24:27]
	v_mfma_f32_16x16x32_bf16 v[20:23], v[202:205], v[174:177], v[20:23]
	v_mfma_f32_16x16x32_bf16 v[16:19], v[210:213], v[174:177], v[16:19]
	v_mfma_f32_16x16x32_bf16 v[12:15], v[202:205], v[182:185], v[12:15]
	v_mfma_f32_16x16x32_bf16 v[8:11], v[210:213], v[182:185], v[8:11]
	v_mfma_f32_16x16x32_bf16 v[4:7], v[202:205], v[194:197], v[4:7]
	v_mfma_f32_16x16x32_bf16 v[0:3], v[210:213], v[194:197], v[0:3]
	v_mfma_f32_16x16x32_bf16 v[28:31], v[206:209], v[170:173], v[28:31]
	v_mfma_f32_16x16x32_bf16 v[24:27], v[214:217], v[170:173], v[24:27]
	v_mfma_f32_16x16x32_bf16 v[20:23], v[206:209], v[178:181], v[20:23]
	v_mfma_f32_16x16x32_bf16 v[16:19], v[214:217], v[178:181], v[16:19]
	v_mfma_f32_16x16x32_bf16 v[12:15], v[206:209], v[186:189], v[12:15]
	v_mfma_f32_16x16x32_bf16 v[8:11], v[214:217], v[186:189], v[8:11]
	v_mfma_f32_16x16x32_bf16 v[4:7], v[206:209], v[198:201], v[4:7]
	v_mfma_f32_16x16x32_bf16 v[0:3], v[214:217], v[198:201], v[0:3]
	s_setprio 0
	s_add_i32 s67, s67, 2
	s_add_u32 s24, s24, 0x100
	s_addc_u32 s25, s25, 0
	s_cmp_gt_u32 s67, 29
	s_barrier
	s_cbranch_scc0 .LBB0_3085
	v_mov_b32_e32 v170, 0xbfb8aa3b
	v_mov_b32_e32 v172, 1.0
	v_mov_b64_e32 v[176:177], 0
	v_mov_b64_e32 v[178:179], 0
	v_pk_mul_f32 v[162:163], v[124:125], v[170:171] op_sel_hi:[1,0]
	s_add_u32 s24, s11, 0xffffff00
	v_pk_mul_f32 v[164:165], v[126:127], v[170:171] op_sel_hi:[1,0]
	s_addc_u32 s25, s64, -1
	v_pk_mul_f32 v[166:167], v[92:93], v[170:171] op_sel_hi:[1,0]
	s_ashr_i32 s11, s10, 31
	v_pk_mul_f32 v[168:169], v[94:95], v[170:171] op_sel_hi:[1,0]
	s_lshl_b64 s[36:37], s[10:11], 8
	v_exp_f32_e32 v162, v162
	v_lshl_add_u64 v[144:145], v[134:135], 0, s[36:37]
	v_exp_f32_e32 v163, v163
	v_mov_b64_e32 v[146:147], s[44:45]
	v_exp_f32_e32 v164, v164
	v_mad_u64_u32 v[146:147], s[38:39], v144, s56, v[146:147]
	v_exp_f32_e32 v165, v165
	s_lshl_b32 s11, s50, 7
	v_exp_f32_e32 v166, v166
	v_mov_b32_e32 v144, v147
	v_exp_f32_e32 v167, v167
	s_or_b32 s36, s11, s51
	v_exp_f32_e32 v168, v168
	v_mad_u64_u32 v[144:145], s[38:39], v145, s56, v[144:145]
	v_exp_f32_e32 v169, v169
	s_ashr_i32 s37, s36, 31
	v_mov_b32_e32 v147, v144
	v_lshl_add_u64 v[144:145], s[36:37], 1, v[146:147]
	v_lshl_add_u64 v[144:145], v[144:145], 0, v[132:133]
	v_pk_add_f32 v[162:163], v[162:163], v[172:173] op_sel_hi:[1,0]
	v_pk_add_f32 v[164:165], v[164:165], v[172:173] op_sel_hi:[1,0]
	v_pk_add_f32 v[166:167], v[166:167], v[172:173] op_sel_hi:[1,0]
	v_pk_add_f32 v[168:169], v[168:169], v[172:173] op_sel_hi:[1,0]
	v_rcp_f32_e32 v162, v162
	v_rcp_f32_e32 v163, v163
	v_rcp_f32_e32 v164, v164
	v_rcp_f32_e32 v165, v165
	v_rcp_f32_e32 v166, v166
	v_rcp_f32_e32 v167, v167
	v_rcp_f32_e32 v168, v168
	v_rcp_f32_e32 v169, v169
	v_pk_mul_f32 v[162:163], v[124:125], v[162:163]
	v_pk_mul_f32 v[164:165], v[126:127], v[164:165]
	v_pk_mul_f32 v[166:167], v[92:93], v[166:167]
	v_pk_mul_f32 v[168:169], v[94:95], v[168:169]
	v_pk_mul_f32 v[162:163], v[120:121], v[162:163]
	v_pk_mul_f32 v[164:165], v[122:123], v[164:165]
	v_pk_mul_f32 v[166:167], v[88:89], v[166:167]
	v_pk_mul_f32 v[168:169], v[90:91], v[168:169]
	v_cvt_pk_bf16_f32 v150, v162, v163
	v_cvt_pk_bf16_f32 v151, v164, v165
	v_cvt_pk_bf16_f32 v152, v166, v167
	v_cvt_pk_bf16_f32 v153, v168, v169
	global_store_dwordx4 v[144:145], v[150:153], off
	v_add_co_u32_e32 v146, vcc, s57, v144
	s_nop 0
	v_addc_co_u32_e32 v147, vcc, 0, v145, vcc
	v_pk_mul_f32 v[162:163], v[116:117], v[170:171] op_sel_hi:[1,0]
	v_pk_mul_f32 v[164:165], v[118:119], v[170:171] op_sel_hi:[1,0]
	v_pk_mul_f32 v[166:167], v[84:85], v[170:171] op_sel_hi:[1,0]
	v_pk_mul_f32 v[168:169], v[86:87], v[170:171] op_sel_hi:[1,0]
	v_exp_f32_e32 v162, v162
	v_exp_f32_e32 v163, v163
	v_exp_f32_e32 v164, v164
	v_exp_f32_e32 v165, v165
	v_exp_f32_e32 v166, v166
	v_exp_f32_e32 v167, v167
	v_exp_f32_e32 v168, v168
	v_exp_f32_e32 v169, v169
	v_pk_add_f32 v[162:163], v[162:163], v[172:173] op_sel_hi:[1,0]
	v_pk_add_f32 v[164:165], v[164:165], v[172:173] op_sel_hi:[1,0]
; __device__ __forceinline__ unsigned cvt_pk_bf16(float lo, float hi) { unsigned r; asm volatile("v_cvt_pk_bf16_f32 %0, %1, %2" : "=v"(r) : "v"(lo), "v"(hi)); return r; }
; template <class Epi>
; __device__ __forceinline__ void gemm_phase(LAS unsigned char* lds, const Gemm g, const Sched& S, const Epi& E) {
;     ...
; #pragma unroll
;         for (int a = 0; a < 2; ++a)
; #pragma unroll
;             for (int b = 0; b < 2; ++b)
; #pragma unroll
;                 for (int m = 0; m < 4; ++m)
; #pragma unroll
;                     for (int n = 0; n < 2; ++n) acc[a][b][m][n] = (f32x4){0.f, 0.f, 0.f, 0.f};
;     __device__ __forceinline__ void operator()(AccRef acc, const Unit& u, int wr, int wc, int fr, int fq) const {
;     ...
;         for (int ai = 0; ai < 2; ++ai)
; #pragma unroll
;             for (int m = 0; m < 4; ++m) { const size_t row = (size_t)u.pm * 256 + ai * 128 + wr * 64 + m * 16 + fr; float o[8];
; #pragma unroll
;                 for (int bj = 0; bj < 2; ++bj) { const f32x4 gg = acc[ai][bj][m][0], uu = acc[ai][bj][m][1];
; #pragma unroll
;                     for (int j = 0; j < 4; ++j) o[4 * bj + j] = gg[j] * __builtin_amdgcn_rcpf(1.0f + __expf(-gg[j])) * uu[j]; }
;                 u32x4 w; w.x = cvt_pk_bf16(o[0], o[1]); w.y = cvt_pk_bf16(o[2], o[3]); w.z = cvt_pk_bf16(o[4], o[5]); w.w = cvt_pk_bf16(o[6], o[7]);
;                 *(u32x4*)(act + row * FF_ + (u.pn * 4 + wc) * 32 + 8 * fq) = w; }
	v_pk_add_f32 v[166:167], v[166:167], v[172:173] op_sel_hi:[1,0]
	v_pk_add_f32 v[168:169], v[168:169], v[172:173] op_sel_hi:[1,0]
	v_rcp_f32_e32 v162, v162
	v_rcp_f32_e32 v163, v163
	v_rcp_f32_e32 v164, v164
	v_rcp_f32_e32 v165, v165
	v_rcp_f32_e32 v166, v166
	v_rcp_f32_e32 v167, v167
	v_rcp_f32_e32 v168, v168
	v_rcp_f32_e32 v169, v169
	v_pk_mul_f32 v[162:163], v[116:117], v[162:163]
	v_pk_mul_f32 v[164:165], v[118:119], v[164:165]
	v_pk_mul_f32 v[166:167], v[84:85], v[166:167]
	v_pk_mul_f32 v[168:169], v[86:87], v[168:169]
	v_pk_mul_f32 v[162:163], v[112:113], v[162:163]
	v_pk_mul_f32 v[164:165], v[114:115], v[164:165]
	v_pk_mul_f32 v[166:167], v[80:81], v[166:167]
	v_pk_mul_f32 v[168:169], v[82:83], v[168:169]
	v_cvt_pk_bf16_f32 v150, v162, v163
	v_cvt_pk_bf16_f32 v151, v164, v165
	v_cvt_pk_bf16_f32 v152, v166, v167
	v_cvt_pk_bf16_f32 v153, v168, v169
	global_store_dwordx4 v[146:147], v[150:153], off
	v_mfma_f32_32x32x16_bf16 v[80:95], v[176:179], v[176:179], 0
	v_mfma_f32_32x32x16_bf16 v[112:127], v[176:179], v[176:179], 0
	v_add_co_u32_e32 v146, vcc, s58, v144
	s_nop 0
	v_addc_co_u32_e32 v147, vcc, 0, v145, vcc
	v_pk_mul_f32 v[162:163], v[108:109], v[170:171] op_sel_hi:[1,0]
	v_pk_mul_f32 v[164:165], v[110:111], v[170:171] op_sel_hi:[1,0]
	v_pk_mul_f32 v[166:167], v[76:77], v[170:171] op_sel_hi:[1,0]
	v_pk_mul_f32 v[168:169], v[78:79], v[170:171] op_sel_hi:[1,0]
	v_exp_f32_e32 v162, v162
	v_exp_f32_e32 v163, v163
	v_exp_f32_e32 v164, v164
	v_exp_f32_e32 v165, v165
	v_exp_f32_e32 v166, v166
	v_exp_f32_e32 v167, v167
	v_exp_f32_e32 v168, v168
	v_exp_f32_e32 v169, v169
	v_pk_add_f32 v[162:163], v[162:163], v[172:173] op_sel_hi:[1,0]
	v_pk_add_f32 v[164:165], v[164:165], v[172:173] op_sel_hi:[1,0]
	v_pk_add_f32 v[166:167], v[166:167], v[172:173] op_sel_hi:[1,0]
	v_pk_add_f32 v[168:169], v[168:169], v[172:173] op_sel_hi:[1,0]
	v_rcp_f32_e32 v162, v162
	v_rcp_f32_e32 v163, v163
	v_rcp_f32_e32 v164, v164
	v_rcp_f32_e32 v165, v165
	v_rcp_f32_e32 v166, v166
	v_rcp_f32_e32 v167, v167
	v_rcp_f32_e32 v168, v168
	v_rcp_f32_e32 v169, v169
	v_pk_mul_f32 v[162:163], v[108:109], v[162:163]
	v_pk_mul_f32 v[164:165], v[110:111], v[164:165]
	v_pk_mul_f32 v[166:167], v[76:77], v[166:167]
	v_pk_mul_f32 v[168:169], v[78:79], v[168:169]
	v_pk_mul_f32 v[162:163], v[104:105], v[162:163]
	v_pk_mul_f32 v[164:165], v[106:107], v[164:165]
	v_pk_mul_f32 v[166:167], v[72:73], v[166:167]
	v_pk_mul_f32 v[168:169], v[74:75], v[168:169]
	v_cvt_pk_bf16_f32 v150, v162, v163
	v_cvt_pk_bf16_f32 v151, v164, v165
	v_cvt_pk_bf16_f32 v152, v166, v167
	v_cvt_pk_bf16_f32 v153, v168, v169
	global_store_dwordx4 v[146:147], v[150:153], off
	v_add_co_u32_e32 v146, vcc, s59, v144
	s_nop 0
	v_addc_co_u32_e32 v147, vcc, 0, v145, vcc
	v_pk_mul_f32 v[162:163], v[100:101], v[170:171] op_sel_hi:[1,0]
	v_pk_mul_f32 v[164:165], v[102:103], v[170:171] op_sel_hi:[1,0]
	v_pk_mul_f32 v[166:167], v[68:69], v[170:171] op_sel_hi:[1,0]
	v_pk_mul_f32 v[168:169], v[70:71], v[170:171] op_sel_hi:[1,0]
	v_exp_f32_e32 v162, v162
	v_exp_f32_e32 v163, v163
	v_exp_f32_e32 v164, v164
	v_exp_f32_e32 v165, v165
	v_exp_f32_e32 v166, v166
	v_exp_f32_e32 v167, v167
	v_exp_f32_e32 v168, v168
	v_exp_f32_e32 v169, v169
	v_pk_add_f32 v[162:163], v[162:163], v[172:173] op_sel_hi:[1,0]
	v_pk_add_f32 v[164:165], v[164:165], v[172:173] op_sel_hi:[1,0]
	v_pk_add_f32 v[166:167], v[166:167], v[172:173] op_sel_hi:[1,0]
	v_pk_add_f32 v[168:169], v[168:169], v[172:173] op_sel_hi:[1,0]
	v_rcp_f32_e32 v162, v162
	v_rcp_f32_e32 v163, v163
	v_rcp_f32_e32 v164, v164
	v_rcp_f32_e32 v165, v165
	v_rcp_f32_e32 v166, v166
	v_rcp_f32_e32 v167, v167
	v_rcp_f32_e32 v168, v168
	v_rcp_f32_e32 v169, v169
	v_pk_mul_f32 v[162:163], v[100:101], v[162:163]
	v_pk_mul_f32 v[164:165], v[102:103], v[164:165]
	v_pk_mul_f32 v[166:167], v[68:69], v[166:167]
	v_pk_mul_f32 v[168:169], v[70:71], v[168:169]
	v_pk_mul_f32 v[162:163], v[96:97], v[162:163]
	v_pk_mul_f32 v[164:165], v[98:99], v[164:165]
	v_pk_mul_f32 v[166:167], v[64:65], v[166:167]
	v_pk_mul_f32 v[168:169], v[66:67], v[168:169]
	v_cvt_pk_bf16_f32 v150, v162, v163
	v_cvt_pk_bf16_f32 v151, v164, v165
	v_cvt_pk_bf16_f32 v152, v166, v167
	v_cvt_pk_bf16_f32 v153, v168, v169
	global_store_dwordx4 v[146:147], v[150:153], off
	v_mfma_f32_32x32x16_bf16 v[64:79], v[176:179], v[176:179], 0
	v_mfma_f32_32x32x16_bf16 v[96:111], v[176:179], v[176:179], 0
	v_add_co_u32_e32 v146, vcc, s60, v144
	s_nop 0
	v_addc_co_u32_e32 v147, vcc, 0, v145, vcc
	v_pk_mul_f32 v[162:163], v[60:61], v[170:171] op_sel_hi:[1,0]
	v_pk_mul_f32 v[164:165], v[62:63], v[170:171] op_sel_hi:[1,0]
	v_pk_mul_f32 v[166:167], v[28:29], v[170:171] op_sel_hi:[1,0]
	v_pk_mul_f32 v[168:169], v[30:31], v[170:171] op_sel_hi:[1,0]
	v_exp_f32_e32 v162, v162
	v_exp_f32_e32 v163, v163
	v_exp_f32_e32 v164, v164
	v_exp_f32_e32 v165, v165
	v_exp_f32_e32 v166, v166
	v_exp_f32_e32 v167, v167
	v_exp_f32_e32 v168, v168
	v_exp_f32_e32 v169, v169
	v_pk_add_f32 v[162:163], v[162:163], v[172:173] op_sel_hi:[1,0]
	v_pk_add_f32 v[164:165], v[164:165], v[172:173] op_sel_hi:[1,0]
	v_pk_add_f32 v[166:167], v[166:167], v[172:173] op_sel_hi:[1,0]
	v_pk_add_f32 v[168:169], v[168:169], v[172:173] op_sel_hi:[1,0]
	v_rcp_f32_e32 v162, v162
	v_rcp_f32_e32 v163, v163
	v_rcp_f32_e32 v164, v164
	v_rcp_f32_e32 v165, v165
	v_rcp_f32_e32 v166, v166
	v_rcp_f32_e32 v167, v167
	v_rcp_f32_e32 v168, v168
	v_rcp_f32_e32 v169, v169
	v_pk_mul_f32 v[162:163], v[60:61], v[162:163]
	v_pk_mul_f32 v[164:165], v[62:63], v[164:165]
	v_pk_mul_f32 v[166:167], v[28:29], v[166:167]
	v_pk_mul_f32 v[168:169], v[30:31], v[168:169]
; __device__ __forceinline__ unsigned cvt_pk_bf16(float lo, float hi) { unsigned r; asm volatile("v_cvt_pk_bf16_f32 %0, %1, %2" : "=v"(r) : "v"(lo), "v"(hi)); return r; }
; template <class Epi>
; __device__ __forceinline__ void gemm_phase(LAS unsigned char* lds, const Gemm g, const Sched& S, const Epi& E) {
;     ...
;         if (!has_next) break;
; #pragma unroll
;         for (int a = 0; a < 2; ++a)
; #pragma unroll
;             for (int b = 0; b < 2; ++b)
; #pragma unroll
;                 for (int m = 0; m < 4; ++m)
; #pragma unroll
;                     for (int n = 0; n < 2; ++n) acc[a][b][m][n] = (f32x4){0.f, 0.f, 0.f, 0.f};
;         cur = nxt; cA = nA; cB = nB; ++ui;
;     __device__ __forceinline__ void operator()(AccRef acc, const Unit& u, int wr, int wc, int fr, int fq) const {
;     ...
;         for (int ai = 0; ai < 2; ++ai)
; #pragma unroll
;             for (int m = 0; m < 4; ++m) { const size_t row = (size_t)u.pm * 256 + ai * 128 + wr * 64 + m * 16 + fr; float o[8];
; #pragma unroll
;                 for (int bj = 0; bj < 2; ++bj) { const f32x4 gg = acc[ai][bj][m][0], uu = acc[ai][bj][m][1];
; #pragma unroll
;                     for (int j = 0; j < 4; ++j) o[4 * bj + j] = gg[j] * __builtin_amdgcn_rcpf(1.0f + __expf(-gg[j])) * uu[j]; }
;                 u32x4 w; w.x = cvt_pk_bf16(o[0], o[1]); w.y = cvt_pk_bf16(o[2], o[3]); w.z = cvt_pk_bf16(o[4], o[5]); w.w = cvt_pk_bf16(o[6], o[7]);
;                 *(u32x4*)(act + row * FF_ + (u.pn * 4 + wc) * 32 + 8 * fq) = w; }
	v_pk_mul_f32 v[162:163], v[56:57], v[162:163]
	v_pk_mul_f32 v[164:165], v[58:59], v[164:165]
	v_pk_mul_f32 v[166:167], v[24:25], v[166:167]
	v_pk_mul_f32 v[168:169], v[26:27], v[168:169]
	v_cvt_pk_bf16_f32 v150, v162, v163
	v_cvt_pk_bf16_f32 v151, v164, v165
	v_cvt_pk_bf16_f32 v152, v166, v167
	v_cvt_pk_bf16_f32 v153, v168, v169
	global_store_dwordx4 v[146:147], v[150:153], off
	v_add_co_u32_e32 v146, vcc, s61, v144
	s_nop 0
	v_addc_co_u32_e32 v147, vcc, 0, v145, vcc
	v_pk_mul_f32 v[162:163], v[52:53], v[170:171] op_sel_hi:[1,0]
	v_pk_mul_f32 v[164:165], v[54:55], v[170:171] op_sel_hi:[1,0]
	v_pk_mul_f32 v[166:167], v[20:21], v[170:171] op_sel_hi:[1,0]
	v_pk_mul_f32 v[168:169], v[22:23], v[170:171] op_sel_hi:[1,0]
	v_exp_f32_e32 v162, v162
	v_exp_f32_e32 v163, v163
	v_exp_f32_e32 v164, v164
	v_exp_f32_e32 v165, v165
	v_exp_f32_e32 v166, v166
	v_exp_f32_e32 v167, v167
	v_exp_f32_e32 v168, v168
	v_exp_f32_e32 v169, v169
	v_pk_add_f32 v[162:163], v[162:163], v[172:173] op_sel_hi:[1,0]
	v_pk_add_f32 v[164:165], v[164:165], v[172:173] op_sel_hi:[1,0]
	v_pk_add_f32 v[166:167], v[166:167], v[172:173] op_sel_hi:[1,0]
	v_pk_add_f32 v[168:169], v[168:169], v[172:173] op_sel_hi:[1,0]
	v_rcp_f32_e32 v162, v162
	v_rcp_f32_e32 v163, v163
	v_rcp_f32_e32 v164, v164
	v_rcp_f32_e32 v165, v165
	v_rcp_f32_e32 v166, v166
	v_rcp_f32_e32 v167, v167
	v_rcp_f32_e32 v168, v168
	v_rcp_f32_e32 v169, v169
	v_pk_mul_f32 v[162:163], v[52:53], v[162:163]
	v_pk_mul_f32 v[164:165], v[54:55], v[164:165]
	v_pk_mul_f32 v[166:167], v[20:21], v[166:167]
	v_pk_mul_f32 v[168:169], v[22:23], v[168:169]
	v_pk_mul_f32 v[162:163], v[48:49], v[162:163]
	v_pk_mul_f32 v[164:165], v[50:51], v[164:165]
	v_pk_mul_f32 v[166:167], v[16:17], v[166:167]
	v_pk_mul_f32 v[168:169], v[18:19], v[168:169]
	v_cvt_pk_bf16_f32 v150, v162, v163
	v_cvt_pk_bf16_f32 v151, v164, v165
	v_cvt_pk_bf16_f32 v152, v166, v167
	v_cvt_pk_bf16_f32 v153, v168, v169
	global_store_dwordx4 v[146:147], v[150:153], off
	v_mfma_f32_32x32x16_bf16 v[16:31], v[176:179], v[176:179], 0
	v_mfma_f32_32x32x16_bf16 v[48:63], v[176:179], v[176:179], 0
	v_add_co_u32_e32 v146, vcc, s62, v144
	s_nop 0
	v_addc_co_u32_e32 v147, vcc, 0, v145, vcc
	v_pk_mul_f32 v[162:163], v[44:45], v[170:171] op_sel_hi:[1,0]
	v_pk_mul_f32 v[164:165], v[46:47], v[170:171] op_sel_hi:[1,0]
	v_pk_mul_f32 v[166:167], v[12:13], v[170:171] op_sel_hi:[1,0]
	v_pk_mul_f32 v[168:169], v[14:15], v[170:171] op_sel_hi:[1,0]
	v_exp_f32_e32 v162, v162
	v_exp_f32_e32 v163, v163
	v_exp_f32_e32 v164, v164
	v_exp_f32_e32 v165, v165
	v_exp_f32_e32 v166, v166
	v_exp_f32_e32 v167, v167
	v_exp_f32_e32 v168, v168
	v_exp_f32_e32 v169, v169
	v_pk_add_f32 v[162:163], v[162:163], v[172:173] op_sel_hi:[1,0]
	v_pk_add_f32 v[164:165], v[164:165], v[172:173] op_sel_hi:[1,0]
	v_pk_add_f32 v[166:167], v[166:167], v[172:173] op_sel_hi:[1,0]
	v_pk_add_f32 v[168:169], v[168:169], v[172:173] op_sel_hi:[1,0]
	v_rcp_f32_e32 v162, v162
	v_rcp_f32_e32 v163, v163
	v_rcp_f32_e32 v164, v164
	v_rcp_f32_e32 v165, v165
	v_rcp_f32_e32 v166, v166
	v_rcp_f32_e32 v167, v167
	v_rcp_f32_e32 v168, v168
	v_rcp_f32_e32 v169, v169
	v_pk_mul_f32 v[162:163], v[44:45], v[162:163]
	v_pk_mul_f32 v[164:165], v[46:47], v[164:165]
	v_pk_mul_f32 v[166:167], v[12:13], v[166:167]
	v_pk_mul_f32 v[168:169], v[14:15], v[168:169]
	v_pk_mul_f32 v[162:163], v[40:41], v[162:163]
	v_pk_mul_f32 v[164:165], v[42:43], v[164:165]
	v_pk_mul_f32 v[166:167], v[8:9], v[166:167]
	v_pk_mul_f32 v[168:169], v[10:11], v[168:169]
	v_cvt_pk_bf16_f32 v150, v162, v163
	v_cvt_pk_bf16_f32 v151, v164, v165
	v_cvt_pk_bf16_f32 v152, v166, v167
	v_cvt_pk_bf16_f32 v153, v168, v169
	global_store_dwordx4 v[146:147], v[150:153], off
	v_add_co_u32_e32 v144, vcc, 0x1e4000, v144
	v_addc_co_u32_e32 v145, vcc, 0, v145, vcc
	s_andn2_b64 vcc, exec, s[8:9]
	v_pk_mul_f32 v[162:163], v[36:37], v[170:171] op_sel_hi:[1,0]
	v_pk_mul_f32 v[164:165], v[38:39], v[170:171] op_sel_hi:[1,0]
	v_pk_mul_f32 v[166:167], v[4:5], v[170:171] op_sel_hi:[1,0]
	v_pk_mul_f32 v[168:169], v[6:7], v[170:171] op_sel_hi:[1,0]
	v_exp_f32_e32 v162, v162
	v_exp_f32_e32 v163, v163
	v_exp_f32_e32 v164, v164
	v_exp_f32_e32 v165, v165
	v_exp_f32_e32 v166, v166
	v_exp_f32_e32 v167, v167
	v_exp_f32_e32 v168, v168
	v_exp_f32_e32 v169, v169
	v_pk_add_f32 v[162:163], v[162:163], v[172:173] op_sel_hi:[1,0]
	v_pk_add_f32 v[164:165], v[164:165], v[172:173] op_sel_hi:[1,0]
	v_pk_add_f32 v[166:167], v[166:167], v[172:173] op_sel_hi:[1,0]
	v_pk_add_f32 v[168:169], v[168:169], v[172:173] op_sel_hi:[1,0]
	v_rcp_f32_e32 v162, v162
	v_rcp_f32_e32 v163, v163
	v_rcp_f32_e32 v164, v164
	v_rcp_f32_e32 v165, v165
	v_rcp_f32_e32 v166, v166
	v_rcp_f32_e32 v167, v167
	v_rcp_f32_e32 v168, v168
	v_rcp_f32_e32 v169, v169
	v_pk_mul_f32 v[162:163], v[36:37], v[162:163]
	v_pk_mul_f32 v[164:165], v[38:39], v[164:165]
	v_pk_mul_f32 v[166:167], v[4:5], v[166:167]
	v_pk_mul_f32 v[168:169], v[6:7], v[168:169]
	v_pk_mul_f32 v[162:163], v[32:33], v[162:163]
	v_pk_mul_f32 v[164:165], v[34:35], v[164:165]
	v_pk_mul_f32 v[166:167], v[0:1], v[166:167]
	v_pk_mul_f32 v[168:169], v[2:3], v[168:169]
	v_cvt_pk_bf16_f32 v150, v162, v163
	v_cvt_pk_bf16_f32 v151, v164, v165
	v_cvt_pk_bf16_f32 v152, v166, v167
	v_cvt_pk_bf16_f32 v153, v168, v169
	global_store_dwordx4 v[144:145], v[150:153], off
	v_mfma_f32_32x32x16_bf16 v[0:15], v[176:179], v[176:179], 0
	v_mfma_f32_32x32x16_bf16 v[32:47], v[176:179], v[176:179], 0
	s_cbranch_vccz .LBB0_3081
	s_mov_b64 s[20:21], s[24:25]
	s_andn2_b64 vcc, exec, s[6:7]
	s_mov_b64 s[24:25], s[20:21]
	s_cbranch_vccnz .LBB0_3082
